# attention: straight-line diagonal fast path, early K/V/table LDS prefetch, PV-first M; Up epilogue conv weights staged via LDS-DMA
# speedup vs baseline: 1.0074x; 1.0074x over previous
;     __host__ __device__ bool next(int i, Unit& u) const {
;         const long L = (long)i * G + c; if (L >= nwg) return false;
;         int wgid = (int)L; { const int q = nwg / NXCD, r = nwg % NXCD, xcd = wgid % NXCD, off = wgid / NXCD; wgid = (xcd < r ? xcd * (q + 1) : r * (q + 1) + (xcd - r) * q) + off; }
;         const int nig = WGM * nN, gid = wgid / nig, fm = gid * WGM, gsz = (nM - fm) < WGM ? (nM - fm) : WGM;
;         u.pm = fm + ((wgid % nig) % gsz); u.pn = (wgid % nig) / gsz; return true;
;     __device__ __forceinline__ void operator()(const f32x4 (&acc)[2][2][4][2], const pg8::Unit& u, int ui, int wr, int wc, int fr, int fq) const {
;     ...
;         for (int n = 0; n < 2; ++n) { w0[n] = *(const f32x4*)(cw + fcol + 4 * n); w1[n] = *(const f32x4*)(cw + FF + fcol + 4 * n); w2[n] = *(const f32x4*)(cw + 2 * FF + fcol + 4 * n); bb[n] = *(const f32x4*)(cb + fcol + 4 * n); }
.LBB0_229:
	v_readlane_b32 s12, v249, 40
	v_readlane_b32 s13, v249, 41
	v_readlane_b32 s36, v249, 36
	v_readlane_b32 s37, v249, 37
	v_and_b32_e32 v236, 7, v210
	v_bfe_u32 v238, v210, 3, 2
	v_bfe_u32 v239, v210, 6, 2
	v_lshlrev_b32_e32 v236, 4, v236
	v_lshl_add_u32 v236, v239, 7, v236
	v_lshl_add_u32 v236, s42, 9, v236
	v_mul_u32_u24_e32 v240, 0x2c00, v238
	v_mov_b32_e32 v237, 0
	v_add_u32_e32 v240, v240, v236
	v_mov_b32_e32 v241, 0
	v_cmp_eq_u32_e32 vcc, 3, v238
	v_lshl_add_u64 v[240:241], s[12:13], 0, v[240:241]
	v_lshl_add_u64 v[236:237], s[36:37], 0, v[236:237]
	s_add_i32 m0, s9, 0x24000
	v_cndmask_b32_e32 v236, v240, v236, vcc
	v_cndmask_b32_e32 v237, v241, v237, vcc
	s_nop 0
	global_load_lds_dwordx4 v[236:237], off
	s_add_i32 s35, s41, 1
	s_mul_i32 s36, s35, s39
	s_mul_hi_u32 s37, s35, s56
	s_add_i32 s37, s37, s36
	s_mul_i32 s36, s35, s56
	s_add_u32 s36, s36, s2
	s_addc_u32 s37, s37, s3
	v_cmp_gt_i64_e32 vcc, s[36:37], v[184:185]
	v_cmp_lt_i64_e64 s[70:71], s[36:37], v[178:179]
	s_cbranch_vccnz .LBB0_231
	s_ashr_i32 s37, s36, 31
	s_lshr_b32 s37, s37, 29
	s_add_i32 s37, s36, s37
	s_ashr_i32 s43, s37, 3
	s_and_b32 s37, s37, -8
	s_sub_i32 s36, s36, s37
	s_cmp_lt_i32 s36, 0
	s_movk_i32 s12, 0x161
	s_cselect_b32 s37, s12, 0x160
	s_mul_i32 s36, s36, s37
	s_add_i32 s36, s36, s43
	s_mul_hi_i32 s37, s36, 0x2e8ba2e9
	s_lshr_b32 s43, s37, 31
	s_ashr_i32 s37, s37, 5
	s_add_i32 s37, s37, s43
	s_lshl_b32 s43, s37, 3
	s_sub_i32 s48, 0x80, s43
	s_min_i32 s48, s48, 8
	s_abs_i32 s49, s48
	v_cvt_f32_u32_e32 v2, s49
	s_sub_i32 s54, 0, s49
	s_mulk_i32 s37, 0xb0
	s_sub_i32 s36, s36, s37
	v_rcp_iflag_f32_e32 v2, v2
	s_abs_i32 s37, s36
	s_xor_b32 s53, s36, s48
	s_ashr_i32 s53, s53, 31
	v_mul_f32_e32 v2, 0x4f7ffffe, v2
	v_cvt_u32_f32_e32 v2, v2
	s_nop 0
	v_readfirstlane_b32 s80, v2
	s_mul_i32 s54, s54, s80
	s_mul_hi_u32 s54, s80, s54
	s_add_i32 s80, s80, s54
	s_mul_hi_u32 s54, s37, s80
	s_mul_i32 s80, s54, s49
	s_sub_i32 s37, s37, s80
	s_add_i32 s81, s54, 1
	s_sub_i32 s80, s37, s49
	s_cmp_ge_u32 s37, s49
	s_cselect_b32 s54, s81, s54
	s_cselect_b32 s37, s80, s37
	s_add_i32 s80, s54, 1
	s_cmp_ge_u32 s37, s49
	s_cselect_b32 s37, s80, s54
	s_xor_b32 s37, s37, s53
	s_sub_i32 s80, s37, s53
	s_mul_i32 s37, s80, s48
	s_sub_i32 s36, s36, s37
	s_add_i32 s82, s43, s36

; #define LAS __attribute__((address_space(3)))
;     __device__ __forceinline__ void operator()(const f32x4 (&acc)[2][2][4][2], const pg8::Unit& u, int ui, int wr, int wc, int fr, int fq) const {
;         const int fcol = u.pn * 128 + wc * 32 + 8 * fq;
;         f32x4 w0[2], w1[2], w2[2], bb[2];
; #pragma unroll
;         for (int n = 0; n < 2; ++n) { w0[n] = *(const f32x4*)(cw + fcol + 4 * n); w1[n] = *(const f32x4*)(cw + FF + fcol + 4 * n); w2[n] = *(const f32x4*)(cw + 2 * FF + fcol + 4 * n); bb[n] = *(const f32x4*)(cb + fcol + 4 * n); }
;         h2 w0h[2][2], w1h[2][2], w2h[2][2], bbh[2][2];
; #pragma unroll
;         for (int n = 0; n < 2; ++n)
; #pragma unroll
;             for (int q = 0; q < 2; ++q) { w0h[n][q] = (h2){(_Float16)w0[n][2 * q], (_Float16)w0[n][2 * q + 1]}; w1h[n][q] = (h2){(_Float16)w1[n][2 * q], (_Float16)w1[n][2 * q + 1]};
;                 w2h[n][q] = (h2){(_Float16)w2[n][2 * q], (_Float16)w2[n][2 * q + 1]}; bbh[n][q] = (h2){(_Float16)bb[n][2 * q], (_Float16)bb[n][2 * q + 1]}; }
;         float rr[2][4];
; #pragma unroll
;         for (int ai = 0; ai < 2; ++ai)
; #pragma unroll
;             for (int m = 0; m < 4; ++m) rr[ai][m] = rs[ui * 256 + ai * 128 + wr * 64 + m * 16 + fr];
;         if (fr >= 14) {
; #pragma unroll
;             for (int ai = 0; ai < 2; ++ai)
; #pragma unroll
;                 for (int n = 0; n < 2; ++n) *(LAS f32x4*)(xch + ((ai * 2 + wr) * 4 + wc) * 64 + (fr - 14) * 32 + 8 * fq + 4 * n) = acc[ai][0][3][n] * rr[ai][3];
;         }
.LBB0_235:
	v_lshl_or_b32 v194, s42, 7, v221
	v_ashrrev_i32_e32 v195, 31, v194
	v_bfe_u32 v236, v210, 4, 2
	v_lshlrev_b64 v[202:203], 2, v[194:195]
	s_add_i32 s12, s9, 0x24000
	v_lshl_add_u32 v162, s41, 10, v208
	v_lshl_add_u32 v236, v236, 5, s12
	ds_read_b128 v[146:149], v236
	ds_read_b128 v[130:133], v236 offset:16
	ds_read_b128 v[150:153], v236 offset:128
	ds_read_b128 v[134:137], v236 offset:144
	ds_read_b128 v[154:157], v236 offset:256
	ds_read_b128 v[138:141], v236 offset:272
	ds_read_b128 v[158:161], v236 offset:384
	ds_read_b128 v[142:145], v236 offset:400
	ds_read2_b32 v[204:205], v162 offset1:16
	ds_read2_b32 v[200:201], v162 offset0:32 offset1:48
	ds_read2_b32 v[198:199], v162 offset0:128 offset1:144
	ds_read2_b32 v[196:197], v162 offset0:160 offset1:176
	s_and_saveexec_b64 s[18:19], s[66:67]
	s_cbranch_execz .LBB0_237
	s_waitcnt lgkmcnt(0)
	v_mov_b32_e32 v166, v201
	v_pk_mul_f32 v[164:165], v[80:81], v[166:167] op_sel_hi:[1,0]
	v_pk_mul_f32 v[162:163], v[78:79], v[166:167] op_sel_hi:[1,0]
	ds_write_b128 v217, v[162:165]
	v_pk_mul_f32 v[164:165], v[72:73], v[166:167] op_sel_hi:[1,0]
	v_pk_mul_f32 v[162:163], v[70:71], v[166:167] op_sel_hi:[1,0]
	v_mov_b32_e32 v166, v197
	ds_write_b128 v218, v[162:165]
	v_pk_mul_f32 v[164:165], v[16:17], v[166:167] op_sel_hi:[1,0]
	v_pk_mul_f32 v[162:163], v[14:15], v[166:167] op_sel_hi:[1,0]
	ds_write_b128 v209, v[162:165] offset:256
	v_pk_mul_f32 v[164:165], v[8:9], v[166:167] op_sel_hi:[1,0]
	v_pk_mul_f32 v[162:163], v[6:7], v[166:167] op_sel_hi:[1,0]
	ds_write_b128 v209, v[162:165] offset:272

;     __device__ __forceinline__ void operator()(const f32x4 (&acc)[2][2][4][2], const pg8::Unit& u, int ui, int wr, int wc, int fr, int fq) const {
;     ...
;             for (int m = 0; m < 4; ++m) {
;                 const int rl = ai * 128 + wr * 64 + m * 16 + fr;
;                 f32x4 a[2], o[2];
; #pragma unroll
;                 for (int n = 0; n < 2; ++n) {
;                     a[n] = acc[ai][0][m][n] * rr[ai][m];
;                     const f32x4 v = acc[ai][1][m][n] * rr[ai][m];
; #pragma unroll
;                     for (int q = 0; q < 2; ++q) {
;                         const int xb = __builtin_bit_cast(int, __builtin_amdgcn_cvt_pkrtz(a[n][2 * q], a[n][2 * q + 1]));
;                         const int t1 = __builtin_amdgcn_mov_dpp(xb, 0x121, 0xf, 0xf, true), t2 = __builtin_amdgcn_mov_dpp(xb, 0x122, 0xf, 0xf, true);
;                         const h2 p1 = __builtin_bit_cast(h2, (fr == 0) ? t1p[n][q] : t1), p2 = __builtin_bit_cast(h2, (fr < 2) ? t2p[n][q] : t2), x2 = __builtin_bit_cast(h2, xb);
;                         t1p[n][q] = t1; t2p[n][q] = t2;
;                         const h2 c = p2 * w0h[n][q] + (p1 * w1h[n][q] + (x2 * w2h[n][q] + bbh[n][q]));
;                         const h2 ea = c * (h2){(_Float16)(-LOG2E), (_Float16)(-LOG2E)};
;                         h2 ex; ex.x = __builtin_exp2f16(ea.x); ex.y = __builtin_exp2f16(ea.y);
;                         const h2 dn = ex + (h2){(_Float16)1.f, (_Float16)1.f};
;                         h2 rc; rc.x = __builtin_amdgcn_rcph(dn.x); rc.y = __builtin_amdgcn_rcph(dn.y);
;                         const h2 sg = c * rc;
;                         o[n][2 * q] = (float)sg.x * v[2 * q]; o[n][2 * q + 1] = (float)sg.y * v[2 * q + 1];
;                     }
;                 }
;                 u32x4 pk; pk.x = cvt_pk_bf16(o[0][0], o[0][1]); pk.y = cvt_pk_bf16(o[0][2], o[0][3]); pk.z = cvt_pk_bf16(o[1][0], o[1][1]); pk.w = cvt_pk_bf16(o[1][2], o[1][3]);
;                 *(u32x4*)(U + (size_t)(u.pm * 256 + rl) * FF + fcol) = pk;
;                 if (ai == 0 && m == 0 && wr == 0 && fr < 2) {
; #pragma unroll
;                     for (int n = 0; n < 2; ++n) { *(f32x4*)(topa + (size_t)(u.pm * 2 + fr) * FF + fcol + 4 * n) = a[n]; *(f32x4*)(topv + (size_t)(u.pm * 2 + fr) * FF + fcol + 4 * n) = acc[0][1][0][n] * rr[0][0]; }
;                 }
.LBB0_239:
	v_cvt_pk_f16_f32 v225, v146, v147
	v_cvt_pk_f16_f32 v146, v130, v131
	v_cvt_pk_f16_f32 v131, v136, v137
	s_waitcnt lgkmcnt(1)
	v_cvt_pkrtz_f16_f32 v136, v162, v163
	v_cvt_pk_f16_f32 v134, v134, v135
	v_cvt_pk_f16_f32 v135, v138, v139
	v_cvt_pk_f16_f32 v130, v132, v133
	v_cvt_pk_f16_f32 v132, v140, v141
	v_mov_b32_dpp v139, v136 row_ror:1 row_mask:0xf bank_mask:0xf bound_ctrl:1
	v_mov_b32_dpp v140, v136 row_ror:2 row_mask:0xf bank_mask:0xf bound_ctrl:1
	v_cvt_pkrtz_f16_f32 v136, v164, v165
	v_pk_mul_f32 v[126:127], v[126:127], v[204:205] op_sel_hi:[1,0]
	v_cvt_pk_f16_f32 v147, v148, v149
	v_cvt_pk_f16_f32 v148, v152, v153
	v_cvt_pk_f16_f32 v138, v142, v143
	v_mov_b32_dpp v141, v136 row_ror:1 row_mask:0xf bank_mask:0xf bound_ctrl:1
	v_mov_b32_dpp v142, v136 row_ror:2 row_mask:0xf bank_mask:0xf bound_ctrl:1
	s_waitcnt lgkmcnt(0)
	v_cvt_pkrtz_f16_f32 v136, v166, v167
	v_cvt_pkrtz_f16_f32 v152, v126, v127
	v_cvt_pk_f16_f32 v154, v154, v155
	v_cvt_pk_f16_f32 v155, v158, v159
	v_cvt_pk_f16_f32 v133, v144, v145
	v_mov_b32_dpp v143, v136 row_ror:1 row_mask:0xf bank_mask:0xf bound_ctrl:1
	v_mov_b32_dpp v144, v136 row_ror:2 row_mask:0xf bank_mask:0xf bound_ctrl:1
	v_mov_b32_dpp v136, v152 row_ror:1 row_mask:0xf bank_mask:0xf bound_ctrl:1
	v_cvt_pk_f16_f32 v151, v150, v151
	v_mov_b32_dpp v137, v152 row_ror:2 row_mask:0xf bank_mask:0xf bound_ctrl:1
	v_cndmask_b32_e64 v139, v136, v139, s[68:69]
	v_pk_fma_f16 v152, v154, v152, v155
	v_cndmask_b32_e64 v140, v137, v140, s[76:77]
	v_pk_fma_f16 v139, v151, v139, v152
	v_pk_mul_f32 v[128:129], v[128:129], v[204:205] op_sel_hi:[1,0]
	v_pk_fma_f16 v152, v225, v140, v139
	v_cvt_pk_f16_f32 v149, v156, v157
	v_pk_mul_f16 v139, v152, s52 op_sel_hi:[1,0]
	v_cvt_pkrtz_f16_f32 v157, v128, v129
	v_exp_f16_e32 v140, v139
	v_exp_f16_sdwa v139, v139 dst_sel:DWORD dst_unused:UNUSED_PAD src0_sel:WORD_1
	v_cvt_pk_f16_f32 v150, v160, v161
	v_pk_mul_f32 v[118:119], v[118:119], v[204:205] op_sel_hi:[1,0]
	v_pk_mul_f32 v[120:121], v[120:121], v[204:205] op_sel_hi:[1,0]
	v_pack_b32_f16 v139, v140, v139
	v_pk_add_f16 v139, v139, 1.0 op_sel_hi:[1,0]
	v_mov_b32_dpp v140, v157 row_ror:2 row_mask:0xf bank_mask:0xf bound_ctrl:1
	v_rcp_f16_e32 v153, v139
	v_rcp_f16_sdwa v156, v139 dst_sel:DWORD dst_unused:UNUSED_PAD src0_sel:WORD_1
	v_mov_b32_dpp v139, v157 row_ror:1 row_mask:0xf bank_mask:0xf bound_ctrl:1
	v_cndmask_b32_e64 v141, v139, v141, s[68:69]
	v_pk_fma_f16 v157, v149, v157, v150
	v_cndmask_b32_e64 v142, v140, v142, s[76:77]
	v_pk_fma_f16 v141, v148, v141, v157
	v_pack_b32_f16 v153, v153, v156
	v_pk_fma_f16 v141, v147, v142, v141
	v_cvt_pkrtz_f16_f32 v145, v168, v169
	v_pk_mul_f16 v142, v141, s52 op_sel_hi:[1,0]
	v_cvt_pkrtz_f16_f32 v159, v120, v121
	v_exp_f16_e32 v157, v142
	v_exp_f16_sdwa v142, v142 dst_sel:DWORD dst_unused:UNUSED_PAD src0_sel:WORD_1
	v_mov_b32_dpp v158, v145 row_ror:1 row_mask:0xf bank_mask:0xf bound_ctrl:1
	v_mov_b32_dpp v145, v145 row_ror:2 row_mask:0xf bank_mask:0xf bound_ctrl:1
	v_pk_mul_f32 v[124:125], v[124:125], v[204:205] op_sel_hi:[1,0]
	v_pack_b32_f16 v142, v157, v142
	v_pk_add_f16 v142, v142, 1.0 op_sel_hi:[1,0]
	v_pk_mul_f16 v153, v152, v153
	v_rcp_f16_e32 v156, v142
	v_rcp_f16_sdwa v142, v142 dst_sel:DWORD dst_unused:UNUSED_PAD src0_sel:WORD_1
	v_cvt_f32_f16_e32 v152, v153
	v_cvt_f32_f16_sdwa v153, v153 dst_sel:DWORD dst_unused:UNUSED_PAD src0_sel:WORD_1
	v_pk_mul_f32 v[122:123], v[122:123], v[204:205] op_sel_hi:[1,0]
	v_pack_b32_f16 v142, v156, v142
	v_cvt_pkrtz_f16_f32 v156, v118, v119
	v_pk_mul_f16 v157, v141, v142
	v_pk_mul_f32 v[152:153], v[122:123], v[152:153]
	v_mov_b32_dpp v141, v156 row_ror:1 row_mask:0xf bank_mask:0xf bound_ctrl:1
	v_mov_b32_dpp v142, v156 row_ror:2 row_mask:0xf bank_mask:0xf bound_ctrl:1
	v_cndmask_b32_e64 v143, v141, v143, s[68:69]
	v_pk_fma_f16 v156, v135, v156, v138
	v_cndmask_b32_e64 v144, v142, v144, s[76:77]
	v_pk_fma_f16 v143, v134, v143, v156
	v_cvt_f32_f16_e32 v156, v157
	v_pk_fma_f16 v160, v146, v144, v143
	v_cvt_f32_f16_sdwa v157, v157 dst_sel:DWORD dst_unused:UNUSED_PAD src0_sel:WORD_1
	v_pk_mul_f16 v143, v160, s52 op_sel_hi:[1,0]
	v_pk_mul_f32 v[114:115], v[114:115], v[204:205] op_sel_hi:[1,0]
	v_exp_f16_e32 v144, v143
	v_exp_f16_sdwa v143, v143 dst_sel:DWORD dst_unused:UNUSED_PAD src0_sel:WORD_1
	v_lshl_add_u32 v224, s40, 8, v206
	v_pk_mul_f32 v[116:117], v[116:117], v[204:205] op_sel_hi:[1,0]
	v_lshl_add_u32 v223, s40, 1, v1
	v_pack_b32_f16 v143, v144, v143
	v_pk_add_f16 v143, v143, 1.0 op_sel_hi:[1,0]
	v_mov_b32_dpp v144, v159 row_ror:2 row_mask:0xf bank_mask:0xf bound_ctrl:1
	v_rcp_f16_e32 v161, v143
	v_rcp_f16_sdwa v162, v143 dst_sel:DWORD dst_unused:UNUSED_PAD src0_sel:WORD_1
	v_mov_b32_dpp v143, v159 row_ror:1 row_mask:0xf bank_mask:0xf bound_ctrl:1
	v_cndmask_b32_e64 v158, v143, v158, s[68:69]
	v_pk_fma_f16 v159, v132, v159, v133
	v_cndmask_b32_e64 v145, v144, v145, s[76:77]
	v_pk_fma_f16 v158, v131, v158, v159
	s_nop 0
	v_pk_fma_f16 v145, v130, v145, v158
	s_nop 0
	v_pk_mul_f16 v158, v145, s52 op_sel_hi:[1,0]
	s_nop 0
	v_exp_f16_e32 v163, v158
	v_exp_f16_sdwa v164, v158 dst_sel:DWORD dst_unused:UNUSED_PAD src0_sel:WORD_1
	v_pk_mul_f32 v[158:159], v[124:125], v[156:157]
	v_pack_b32_f16 v156, v161, v162
	v_pack_b32_f16 v157, v163, v164
	v_pk_add_f16 v157, v157, 1.0 op_sel_hi:[1,0]
	s_nop 0
	v_rcp_f16_e32 v161, v157
	v_rcp_f16_sdwa v162, v157 dst_sel:DWORD dst_unused:UNUSED_PAD src0_sel:WORD_1
	v_pk_mul_f16 v157, v160, v156
	v_pack_b32_f16 v160, v161, v162
	v_cvt_f32_f16_e32 v156, v157
	v_cvt_f32_f16_sdwa v157, v157 dst_sel:DWORD dst_unused:UNUSED_PAD src0_sel:WORD_1
	v_pk_mul_f16 v145, v145, v160
	v_pk_mul_f32 v[162:163], v[114:115], v[156:157]
	v_cvt_f32_f16_e32 v160, v145
	v_cvt_f32_f16_sdwa v161, v145 dst_sel:DWORD dst_unused:UNUSED_PAD src0_sel:WORD_1
	v_cvt_pk_bf16_f32 v156, v152, v153
	v_mov_b64_e32 v[152:153], s[50:51]
	v_mad_i64_i32 v[152:153], s[20:21], v224, s38, v[152:153]
	v_pk_mul_f32 v[160:161], v[116:117], v[160:161]
	v_cvt_pk_bf16_f32 v157, v158, v159
	v_cvt_pk_bf16_f32 v158, v162, v163
	v_cvt_pk_bf16_f32 v159, v160, v161
	v_lshl_add_u64 v[152:153], v[194:195], 1, v[152:153]
	global_store_dwordx4 v[152:153], v[156:159], off
	s_and_saveexec_b64 s[20:21], s[18:19]
	s_cbranch_execz .LBB0_241
	s_movk_i32 s12, 0x2c00
	v_mov_b64_e32 v[156:157], s[58:59]
	v_mov_b64_e32 v[152:153], s[94:95]
	v_mad_i64_i32 v[156:157], s[18:19], v223, s12, v[156:157]
	v_mad_i64_i32 v[152:153], s[18:19], v223, s12, v[152:153]
	v_lshl_add_u64 v[156:157], v[156:157], 0, v[202:203]
	v_lshl_add_u64 v[152:153], v[152:153], 0, v[202:203]
	global_store_dwordx4 v[156:157], v[126:129], off
	global_store_dwordx4 v[152:153], v[122:125], off
	global_store_dwordx4 v[156:157], v[118:121], off offset:16
	global_store_dwordx4 v[152:153], v[114:117], off offset:16

; #define ATT_BAR() do { asm volatile("s_waitcnt lgkmcnt(0)" ::: "memory"); __builtin_amdgcn_s_barrier(); asm volatile("" ::: "memory"); } while (0)
; #define ATT_LD(j, KR, VR) do { KR = *(const u32x4*)(Kb + (kg0 + (long)(j) * 64 * D)); VR = *(const u32x4*)(Vt + (vg0 + (long)(j) * 64)); } while (0)
; #define ATT_ST(j, KR, VR) do { LAS unsigned char* kd_ = lds + ATT_KS + ((j) & 3) * KS_TILE + lr * KS_PITCH + pc * 16; LAS unsigned char* vd_ = lds + ATT_VS + ((j) & 3) * VS_TILE + lr * VS_PITCH + (pc >> 1) * 32 + (pc & 1) * 8;     \
;         *(LAS u32x4*)kd_ = KR; *(LAS u32x2*)vd_ = (u32x2){VR.x, VR.y}; *(LAS u32x2*)(vd_ + 16) = (u32x2){VR.z, VR.w}; } while (0)
; __device__ __forceinline__ void attn_phase(LAS unsigned char* lds, const bf16_t* Q, const bf16_t* Kb, const bf16_t* Vt, bf16_t* O, const float* relb, const float* qn, const float* kn, int vcu, int G) {
;     ...
;         const int jlo = (qb < 2) ? 8 - 4 * qb : 0;
;         const long kg0 = ((long)rowbase + (long)(4 * qb - 8) * 64 + lr) * D + h * 64 + pc * 8;
;         const long vg0 = (long)(h * 64 + lr) * M + (long)rowbase + (long)(4 * qb - 8) * 64 + pc * 8;
;         u32x4 kreg, vreg;
;         { u32x4 ka, va, kb2, vb2; ATT_LD(jlo, ka, va); ATT_LD(jlo + 1, kb2, vb2); ATT_LD(jlo + 2, kreg, vreg);
;           ATT_ST(jlo, ka, va); ATT_ST(jlo + 1, kb2, vb2); }
;         bf16x8 qr[4];
;         { const bf16_t* qp = Q + (rowbase + (size_t)qb * 256 + w * 32 + r32) * D + h * 64 + hi * 8;
; #pragma unroll
;           for (int d0 = 0; d0 < 4; ++d0) qr[d0] = *(const bf16x8*)(qp + d0 * 16); }
;         __syncthreads();
;         float lrun = 0.f; f32x16 o0 = {}, o1 = {}, sc0 = {}, sc1 = {}; bf16x8 pw[4] = {};
;         if (half == 1) ATT_BAR();
.LBB0_450:
	s_and_b32 s53, s34, 31
	s_ashr_i32 s18, s34, 9
	s_ashr_i32 s19, s18, 31
	s_lshl_b32 s35, s53, 2
	s_lshl_b64 s[20:21], s[18:19], 13
	s_sub_i32 s40, 8, s35
	s_cmp_lt_u32 s53, 2
	s_cselect_b32 s40, s40, 0
	s_add_i32 s48, s35, -8
	s_ashr_i32 s49, s48, 31
	s_lshl_b64 s[76:77], s[48:49], 6
	s_add_u32 s76, s76, s20
	s_addc_u32 s77, s77, s21
	s_lshl_b32 s35, s43, 6
	v_lshl_add_u64 v[2:3], s[76:77], 0, v[122:123]
	v_add_u32_e32 v6, s35, v122
	v_readlane_b32 s12, v252, 51
	v_ashrrev_i32_e32 v7, 31, v6
	v_lshlrev_b64 v[2:3], 11, v[2:3]
	v_readlane_b32 s13, v252, 52
	s_lshl_b32 s54, s43, 7
	v_lshlrev_b64 v[6:7], 16, v[6:7]
	v_lshl_add_u64 v[2:3], s[12:13], 0, v[2:3]
	v_lshl_add_u64 v[2:3], v[2:3], 0, s[54:55]
	v_mov_b32_e32 v131, v0
	v_lshl_add_u64 v[6:7], s[60:61], 0, v[6:7]
	s_lshl_b64 s[78:79], s[18:19], 14
	v_lshl_add_u64 v[140:141], v[2:3], 0, v[130:131]
	v_lshl_add_u64 v[6:7], v[6:7], 0, s[78:79]
	s_lshl_b64 s[48:49], s[48:49], 7
	v_lshl_add_u64 v[6:7], v[6:7], 0, s[48:49]
	s_lshl_b32 s48, s53, 8
	s_or_b32 s20, s20, s48
	v_lshl_add_u64 v[138:139], v[6:7], 0, v[130:131]
	v_lshl_add_u64 v[38:39], s[20:21], 0, v[124:125]
	v_mov_b32_e32 v133, v0
	s_mov_b32 s81, s55
	v_lshlrev_b64 v[136:137], 10, v[38:39]
	v_lshlrev_b64 v[38:39], 11, v[38:39]
	v_lshl_add_u64 v[38:39], s[64:65], 0, v[38:39]
	v_lshl_add_u64 v[38:39], v[38:39], 0, s[54:55]
	v_lshl_add_u64 v[38:39], v[38:39], 0, v[132:133]
	s_cmp_lg_u32 s40, 0
	s_cbranch_scc1 .Lap_jnz
	global_load_dwordx4 v[2:5], v[140:141], off
	v_lshl_add_u64 v[140:141], v[140:141], 0, s[44:45]
	global_load_dwordx4 v[6:9], v[138:139], off
	global_load_dwordx4 v[10:13], v[140:141], off
	v_lshl_add_u64 v[140:141], v[140:141], 0, s[44:45]
	global_load_dwordx4 v[14:17], v[138:139], off offset:128
	global_load_dwordx4 v[18:21], v[140:141], off
	v_lshl_add_u64 v[140:141], v[140:141], 0, s[44:45]
	global_load_dwordx4 v[22:25], v[138:139], off offset:256
	global_load_dwordx4 v[26:29], v[140:141], off
	v_lshl_add_u64 v[140:141], v[140:141], 0, s[44:45]
	global_load_dwordx4 v[30:33], v[138:139], off offset:384
	global_load_dwordx4 v[34:37], v[140:141], off
	v_lshl_add_u64 v[140:141], v[140:141], 0, s[44:45]
	global_load_dwordx4 v[80:83], v[38:39], off
	global_load_dwordx4 v[84:87], v[38:39], off offset:32
	global_load_dwordx4 v[88:91], v[38:39], off offset:64
	global_load_dwordx4 v[92:95], v[38:39], off offset:96
	global_load_dwordx4 v[226:229], v[140:141], off
	global_load_dwordx4 v[222:225], v[138:139], off offset:512
	v_lshl_add_u64 v[140:141], v[140:141], 0, s[44:45]
	global_load_dwordx4 v[96:99], v[140:141], off
	global_load_dwordx4 v[230:233], v[138:139], off offset:640
	v_lshl_add_u64 v[140:141], v[140:141], 0, s[44:45]
	global_load_dwordx4 v[218:221], v[140:141], off
	global_load_dwordx4 v[100:103], v[138:139], off offset:768
	v_lshl_add_u64 v[140:141], v[140:141], 0, s[44:45]
	s_movk_i32 s80, 0x380
	v_lshl_add_u64 v[138:139], v[138:139], 0, s[80:81]
	v_add_u32_e32 v255, 0x17400, v151
	s_waitcnt vmcnt(18)
	ds_write_b128 v151, v[2:5]
	s_waitcnt vmcnt(17)
	v_add_u32_e32 v1, 0x9000, v152
	ds_write2_b64 v1, v[6:7], v[8:9] offset1:2
	s_waitcnt vmcnt(16)
	ds_write_b128 v151, v[10:13] offset:9216
	s_waitcnt vmcnt(15)
	v_add_u32_e32 v1, 0xb400, v152
	ds_write2_b64 v1, v[14:15], v[16:17] offset1:2
	s_waitcnt vmcnt(14)
	ds_write_b128 v151, v[18:21] offset:18432
	s_waitcnt vmcnt(13)
	v_add_u32_e32 v1, 0xd800, v152
	ds_write2_b64 v1, v[22:23], v[24:25] offset1:2
	s_waitcnt vmcnt(12)
	ds_write_b128 v151, v[26:29] offset:27648
	s_waitcnt vmcnt(11)
	v_add_u32_e32 v1, 0xfc00, v152
	ds_write2_b64 v1, v[30:31], v[32:33] offset1:2
	s_waitcnt vmcnt(10)
	ds_write_b128 v255, v[34:37]
	s_lshr_b32 s49, s43, 3
	s_mulk_i32 s49, 0x2900
	s_add_i32 s49, s49, 0x12000
	v_add_u32_e32 v133, s49, v148
	v_add_u32_e32 v133, v133, v149
	v_mov_b32_e32 v48, v0
	v_mov_b32_e32 v49, v0
	v_mov_b64_e32 v[50:51], v[48:49]
	v_mov_b64_e32 v[52:53], v[48:49]
	v_mov_b64_e32 v[54:55], v[48:49]
	v_mov_b64_e32 v[56:57], v[48:49]
	v_mov_b64_e32 v[58:59], v[48:49]
	v_mov_b64_e32 v[60:61], v[48:49]
	v_mov_b64_e32 v[62:63], v[48:49]
	v_mov_b64_e32 v[64:65], v[48:49]
	v_mov_b64_e32 v[66:67], v[48:49]
	v_mov_b64_e32 v[68:69], v[48:49]
	v_mov_b64_e32 v[70:71], v[48:49]
	v_mov_b64_e32 v[72:73], v[48:49]
	v_mov_b64_e32 v[74:75], v[48:49]
	v_mov_b64_e32 v[76:77], v[48:49]
	v_mov_b64_e32 v[78:79], v[48:49]
	s_waitcnt vmcnt(6) lgkmcnt(0)
	s_cmp_eq_u32 s9, 0
	s_cbranch_scc1 .Lf_cw0
	s_cmp_eq_u32 s9, 1
	s_cbranch_scc1 .Lf_cw1
	s_cmp_eq_u32 s9, 2
	s_cbranch_scc1 .Lf_cw2
.Lf_cw3:
	v_add_u32_e32 v12, 0x6c00, v153
	v_add_u32_e32 v128, 0xfc00, v153
	v_add_u32_e32 v13, 0x17400, v153
	v_add_u32_e32 v129, 0x1bc00, v153
	v_add_u32_e32 v14, 0x19800, v153
	v_add_u32_e32 v157, 0x1e000, v153
	v_add_u32_e32 v15, 0x0, v153
	v_add_u32_e32 v217, 0x9000, v153
	v_add_u32_e32 v126, 0x2400, v153
	v_add_u32_e32 v253, 0xb400, v153
	v_add_u32_e32 v127, 0x4800, v153
	v_add_u32_e32 v254, 0xd800, v153
	s_branch .Lf_go
.Lf_cw2:
	v_add_u32_e32 v12, 0x4800, v153
	v_add_u32_e32 v128, 0xd800, v153
	v_add_u32_e32 v13, 0x6c00, v153
	v_add_u32_e32 v129, 0xfc00, v153
	v_add_u32_e32 v14, 0x17400, v153
	v_add_u32_e32 v157, 0x1bc00, v153
	v_add_u32_e32 v15, 0x19800, v153
	v_add_u32_e32 v217, 0x1e000, v153
	v_add_u32_e32 v126, 0x0, v153
	v_add_u32_e32 v253, 0x9000, v153
	v_add_u32_e32 v127, 0x2400, v153
	v_add_u32_e32 v254, 0xb400, v153
	s_branch .Lf_go
.Lf_cw1:
	v_add_u32_e32 v12, 0x2400, v153
	v_add_u32_e32 v128, 0xb400, v153
	v_add_u32_e32 v13, 0x4800, v153
	v_add_u32_e32 v129, 0xd800, v153
	v_add_u32_e32 v14, 0x6c00, v153
	v_add_u32_e32 v157, 0xfc00, v153
	v_add_u32_e32 v15, 0x17400, v153
	v_add_u32_e32 v217, 0x1bc00, v153
	v_add_u32_e32 v126, 0x19800, v153
	v_add_u32_e32 v253, 0x1e000, v153
	v_add_u32_e32 v127, 0x0, v153
	v_add_u32_e32 v254, 0x9000, v153
	s_branch .Lf_go
; #define ATT_BAR() do { asm volatile("s_waitcnt lgkmcnt(0)" ::: "memory"); __builtin_amdgcn_s_barrier(); asm volatile("" ::: "memory"); } while (0)
; #define ATT_LD(j, KR, VR) do { KR = *(const u32x4*)(Kb + (kg0 + (long)(j) * 64 * D)); VR = *(const u32x4*)(Vt + (vg0 + (long)(j) * 64)); } while (0)
; #define ATT_ST(j, KR, VR) do { LAS unsigned char* kd_ = lds + ATT_KS + ((j) & 3) * KS_TILE + lr * KS_PITCH + pc * 16; LAS unsigned char* vd_ = lds + ATT_VS + ((j) & 3) * VS_TILE + lr * VS_PITCH + (pc >> 1) * 32 + (pc & 1) * 8;     \
;         *(LAS u32x4*)kd_ = KR; *(LAS u32x2*)vd_ = (u32x2){VR.x, VR.y}; *(LAS u32x2*)(vd_ + 16) = (u32x2){VR.z, VR.w}; } while (0)
; __device__ __forceinline__ void attn_phase(LAS unsigned char* lds, const bf16_t* Q, const bf16_t* Kb, const bf16_t* Vt, bf16_t* O, const float* relb, const float* qn, const float* kn, int vcu, int G) {
;     ...
;         for (int g = jlo; g <= 12; ++g) {
;             const int bcg = g - cw, bcp = bcg - 1;
;             const bool actg = (g <= 11) && bcg >= 0 && bcg <= 8, actp = (g - 1 >= jlo) && bcp >= 0 && bcp <= 8;
;             if (actg) ATT_QK(g, bcg, sc0, sc1);
;             if (actp) ATT_PV(g - 1, pw);
;             ATT_BAR();
;             if (g + 2 <= 11) ATT_ST(g + 2, kreg, vreg);
;             if (g + 3 <= 11) ATT_LD(g + 3, kreg, vreg);
;             if (actg) ATT_SM(sc0, sc1, pw);
;             ATT_BAR();
;         }
.Lf_cw0:
	v_add_u32_e32 v12, 0x0, v153
	v_add_u32_e32 v128, 0x9000, v153
	v_add_u32_e32 v13, 0x2400, v153
	v_add_u32_e32 v129, 0xb400, v153
	v_add_u32_e32 v14, 0x4800, v153
	v_add_u32_e32 v157, 0xd800, v153
	v_add_u32_e32 v15, 0x6c00, v153
	v_add_u32_e32 v217, 0xfc00, v153
	v_add_u32_e32 v126, 0x17400, v153
	v_add_u32_e32 v253, 0x1bc00, v153
	v_add_u32_e32 v127, 0x19800, v153
	v_add_u32_e32 v254, 0x1e000, v153
.Lf_go:
	v_mov_b32_e32 v1, s49
	s_barrier
	ds_read_b32 v246, v1
	s_waitcnt lgkmcnt(0)
	v_mov_b32_e32 v247, v246
	ds_read_b128 v[2:5], v12
	ds_read_b128 v[6:9], v12 offset:4608
	ds_read_b128 v[158:161], v12 offset:32
	ds_read_b128 v[162:165], v12 offset:4640
	ds_read_b128 v[166:169], v12 offset:64
	ds_read_b128 v[194:197], v12 offset:4672
	ds_read_b128 v[198:201], v12 offset:96
	ds_read_b128 v[202:205], v12 offset:4704
	v_mov_b64_e32 v[16:17], v[246:247]
	v_mov_b64_e32 v[18:19], v[246:247]
	v_mov_b64_e32 v[20:21], v[246:247]
	v_mov_b64_e32 v[22:23], v[246:247]
	v_mov_b64_e32 v[24:25], v[246:247]
	v_mov_b64_e32 v[26:27], v[246:247]
	v_mov_b64_e32 v[28:29], v[246:247]
	v_mov_b64_e32 v[30:31], v[246:247]
	v_mov_b64_e32 v[32:33], v[246:247]
	v_mov_b64_e32 v[34:35], v[246:247]
	v_mov_b64_e32 v[36:37], v[246:247]
	v_mov_b64_e32 v[38:39], v[246:247]
	v_mov_b64_e32 v[40:41], v[246:247]
	v_mov_b64_e32 v[42:43], v[246:247]
	v_mov_b64_e32 v[44:45], v[246:247]
	v_mov_b64_e32 v[46:47], v[246:247]
	s_andn2_b64 vcc, exec, s[0:1]
	s_cbranch_vccnz .Lf_m0
	s_barrier
.Lf_m0:
	s_waitcnt lgkmcnt(0)
	v_mfma_f32_32x32x16_bf16 v[16:31], v[2:5], v[80:83], v[16:31]
	v_mfma_f32_32x32x16_bf16 v[32:47], v[6:9], v[80:83], v[32:47]
	v_mfma_f32_32x32x16_bf16 v[16:31], v[158:161], v[84:87], v[16:31]
	v_mfma_f32_32x32x16_bf16 v[32:47], v[162:165], v[84:87], v[32:47]
	v_mfma_f32_32x32x16_bf16 v[16:31], v[166:169], v[88:91], v[16:31]
	v_mfma_f32_32x32x16_bf16 v[32:47], v[194:197], v[88:91], v[32:47]
	v_mfma_f32_32x32x16_bf16 v[16:31], v[198:201], v[92:95], v[16:31]
	v_mfma_f32_32x32x16_bf16 v[32:47], v[202:205], v[92:95], v[32:47]
	s_nop 4
	s_waitcnt lgkmcnt(0)
	s_barrier
	s_waitcnt vmcnt(4)
	ds_write_b128 v255, v[226:229] offset:9216
	v_add_u32_e32 v1, 0x1bc00, v152
	ds_write2_b64 v1, v[222:223], v[224:225] offset1:2
	global_load_dwordx4 v[226:229], v[140:141], off
	v_lshl_add_u64 v[140:141], v[140:141], 0, s[44:45]
	global_load_dwordx4 v[222:225], v[138:139], off
	v_lshl_add_u64 v[138:139], v[138:139], 0, s[62:63]
	ds_read_b128 v[2:5], v13
	ds_read_b128 v[6:9], v13 offset:4608
	ds_read_b128 v[158:161], v13 offset:32
	ds_read_b128 v[162:165], v13 offset:4640
	ds_read_b128 v[166:169], v13 offset:64
	ds_read_b128 v[194:197], v13 offset:4672
	ds_read_b128 v[198:201], v13 offset:96
	ds_read_b128 v[202:205], v13 offset:4704
	ds_read_b128 v[234:237], v128
	ds_read_b128 v[238:241], v128 offset:4608
	ds_read_b128 v[242:245], v128 offset:32
	v_exp_f32_e32 v32, v32
	v_exp_f32_e32 v33, v33
	v_exp_f32_e32 v34, v34
	v_exp_f32_e32 v35, v35
	v_exp_f32_e32 v36, v36
	v_add_f32_e32 v10, 0, v32
	v_exp_f32_e32 v37, v37
	v_add_f32_e32 v10, v10, v33
	v_exp_f32_e32 v38, v38
	v_add_f32_e32 v10, v10, v34
	v_exp_f32_e32 v39, v39
	v_add_f32_e32 v10, v10, v35
	v_exp_f32_e32 v40, v40
	v_add_f32_e32 v10, v10, v36
	v_exp_f32_e32 v41, v41
	v_add_f32_e32 v10, v10, v37
	v_exp_f32_e32 v42, v42
	v_add_f32_e32 v10, v10, v38
	v_exp_f32_e32 v43, v43
	v_add_f32_e32 v10, v10, v39
	v_exp_f32_e32 v44, v44
	v_add_f32_e32 v10, v10, v40
	v_exp_f32_e32 v45, v45
	v_add_f32_e32 v10, v10, v41
	v_exp_f32_e32 v46, v46
	v_add_f32_e32 v10, v10, v42
	v_exp_f32_e32 v47, v47
	v_add_f32_e32 v10, v10, v43
	v_add_f32_e32 v10, v10, v44
	v_add_f32_e32 v10, v10, v45
	v_add_f32_e32 v10, v10, v46
	v_add_f32_e32 v10, v10, v47
	v_cvt_pk_bf16_f32 v108, v32, v33
	v_cvt_pk_bf16_f32 v109, v34, v35
	v_cvt_pk_bf16_f32 v110, v36, v37
	v_cvt_pk_bf16_f32 v111, v38, v39
	v_cvt_pk_bf16_f32 v116, v40, v41
	v_cvt_pk_bf16_f32 v117, v42, v43
	v_cvt_pk_bf16_f32 v118, v44, v45
	v_cvt_pk_bf16_f32 v119, v46, v47
	v_mov_b64_e32 v[32:33], v[246:247]
	v_mov_b64_e32 v[34:35], v[246:247]
	v_mov_b64_e32 v[36:37], v[246:247]
	v_mov_b64_e32 v[38:39], v[246:247]
	v_mov_b64_e32 v[40:41], v[246:247]
	v_mov_b64_e32 v[42:43], v[246:247]
	v_mov_b64_e32 v[44:45], v[246:247]
	v_mov_b64_e32 v[46:47], v[246:247]
	v_exp_f32_e32 v16, v16
	v_exp_f32_e32 v17, v17
	v_exp_f32_e32 v18, v18
	v_exp_f32_e32 v19, v19
	v_exp_f32_e32 v20, v20
	v_add_f32_e32 v11, 0, v16
	v_exp_f32_e32 v21, v21
	v_add_f32_e32 v11, v11, v17
	v_exp_f32_e32 v22, v22
	v_add_f32_e32 v11, v11, v18
	v_exp_f32_e32 v23, v23
	v_add_f32_e32 v11, v11, v19
	v_exp_f32_e32 v24, v24
	v_add_f32_e32 v11, v11, v20
	v_exp_f32_e32 v25, v25
	v_add_f32_e32 v11, v11, v21
	v_exp_f32_e32 v26, v26
	v_add_f32_e32 v11, v11, v22
	v_exp_f32_e32 v27, v27
	v_add_f32_e32 v11, v11, v23
	v_exp_f32_e32 v28, v28
	v_add_f32_e32 v11, v11, v24
	v_exp_f32_e32 v29, v29
	v_add_f32_e32 v11, v11, v25
	v_exp_f32_e32 v30, v30
	v_add_f32_e32 v11, v11, v26
	v_exp_f32_e32 v31, v31
	v_add_f32_e32 v11, v11, v27
	v_add_f32_e32 v11, v11, v28
	v_add_f32_e32 v11, v11, v29
	v_add_f32_e32 v11, v11, v30
	v_add_f32_e32 v11, v11, v31
	v_cvt_pk_bf16_f32 v104, v16, v17
	v_cvt_pk_bf16_f32 v105, v18, v19
	v_cvt_pk_bf16_f32 v106, v20, v21
	v_cvt_pk_bf16_f32 v107, v22, v23
	v_cvt_pk_bf16_f32 v112, v24, v25
	v_cvt_pk_bf16_f32 v113, v26, v27
	v_cvt_pk_bf16_f32 v114, v28, v29
	v_cvt_pk_bf16_f32 v115, v30, v31
	v_mov_b64_e32 v[16:17], v[246:247]
	v_mov_b64_e32 v[18:19], v[246:247]
	v_mov_b64_e32 v[20:21], v[246:247]
	v_mov_b64_e32 v[22:23], v[246:247]
	v_mov_b64_e32 v[24:25], v[246:247]
	v_mov_b64_e32 v[26:27], v[246:247]
	v_mov_b64_e32 v[28:29], v[246:247]
	v_mov_b64_e32 v[30:31], v[246:247]
	v_add_f32_e32 v1, v10, v11
	v_add_f32_e32 v131, v131, v1
	s_barrier
; #define ATT_BAR() do { asm volatile("s_waitcnt lgkmcnt(0)" ::: "memory"); __builtin_amdgcn_s_barrier(); asm volatile("" ::: "memory"); } while (0)
; #define ATT_LD(j, KR, VR) do { KR = *(const u32x4*)(Kb + (kg0 + (long)(j) * 64 * D)); VR = *(const u32x4*)(Vt + (vg0 + (long)(j) * 64)); } while (0)
; #define ATT_ST(j, KR, VR) do { LAS unsigned char* kd_ = lds + ATT_KS + ((j) & 3) * KS_TILE + lr * KS_PITCH + pc * 16; LAS unsigned char* vd_ = lds + ATT_VS + ((j) & 3) * VS_TILE + lr * VS_PITCH + (pc >> 1) * 32 + (pc & 1) * 8;     \
;         *(LAS u32x4*)kd_ = KR; *(LAS u32x2*)vd_ = (u32x2){VR.x, VR.y}; *(LAS u32x2*)(vd_ + 16) = (u32x2){VR.z, VR.w}; } while (0)
; __device__ __forceinline__ void attn_phase(LAS unsigned char* lds, const bf16_t* Q, const bf16_t* Kb, const bf16_t* Vt, bf16_t* O, const float* relb, const float* qn, const float* kn, int vcu, int G) {
;     ...
;         for (int g = jlo; g <= 12; ++g) {
;             const int bcg = g - cw, bcp = bcg - 1;
;             const bool actg = (g <= 11) && bcg >= 0 && bcg <= 8, actp = (g - 1 >= jlo) && bcp >= 0 && bcp <= 8;
;             if (actg) ATT_QK(g, bcg, sc0, sc1);
;             if (actp) ATT_PV(g - 1, pw);
;             ATT_BAR();
;             if (g + 2 <= 11) ATT_ST(g + 2, kreg, vreg);
;             if (g + 3 <= 11) ATT_LD(g + 3, kreg, vreg);
;             if (actg) ATT_SM(sc0, sc1, pw);
;             ATT_BAR();
;         }
	s_waitcnt lgkmcnt(0)
	v_mfma_f32_32x32x16_bf16 v[64:79], v[234:237], v[104:107], v[64:79]
	v_mfma_f32_32x32x16_bf16 v[48:63], v[238:241], v[104:107], v[48:63]
	v_mfma_f32_32x32x16_bf16 v[64:79], v[242:245], v[112:115], v[64:79]
	s_waitcnt lgkmcnt(0)
	v_mfma_f32_32x32x16_bf16 v[16:31], v[2:5], v[80:83], v[16:31]
	ds_read_b128 v[2:5], v128 offset:4640
	v_mfma_f32_32x32x16_bf16 v[32:47], v[6:9], v[80:83], v[32:47]
	ds_read_b128 v[6:9], v128 offset:64
	v_mfma_f32_32x32x16_bf16 v[16:31], v[158:161], v[84:87], v[16:31]
	ds_read_b128 v[158:161], v128 offset:4672
	v_mfma_f32_32x32x16_bf16 v[32:47], v[162:165], v[84:87], v[32:47]
	ds_read_b128 v[162:165], v128 offset:96
	v_mfma_f32_32x32x16_bf16 v[16:31], v[166:169], v[88:91], v[16:31]
	ds_read_b128 v[166:169], v128 offset:4704
	v_mfma_f32_32x32x16_bf16 v[32:47], v[194:197], v[88:91], v[32:47]
	v_mfma_f32_32x32x16_bf16 v[16:31], v[198:201], v[92:95], v[16:31]
	v_mfma_f32_32x32x16_bf16 v[32:47], v[202:205], v[92:95], v[32:47]
	s_waitcnt lgkmcnt(4)
	v_mfma_f32_32x32x16_bf16 v[48:63], v[2:5], v[112:115], v[48:63]
	s_waitcnt lgkmcnt(3)
	v_mfma_f32_32x32x16_bf16 v[64:79], v[6:9], v[108:111], v[64:79]
	s_waitcnt lgkmcnt(2)
	v_mfma_f32_32x32x16_bf16 v[48:63], v[158:161], v[108:111], v[48:63]
	s_waitcnt lgkmcnt(1)
	v_mfma_f32_32x32x16_bf16 v[64:79], v[162:165], v[116:119], v[64:79]
	s_waitcnt lgkmcnt(0)
	v_mfma_f32_32x32x16_bf16 v[48:63], v[166:169], v[116:119], v[48:63]
	s_waitcnt lgkmcnt(0)
	s_barrier
	s_waitcnt vmcnt(4)
	ds_write_b128 v151, v[96:99]
	v_add_u32_e32 v1, 0x1e000, v152
	ds_write2_b64 v1, v[230:231], v[232:233] offset1:2
	global_load_dwordx4 v[96:99], v[140:141], off
	v_lshl_add_u64 v[140:141], v[140:141], 0, s[44:45]
	global_load_dwordx4 v[230:233], v[138:139], off
	v_lshl_add_u64 v[138:139], v[138:139], 0, s[62:63]
	ds_read_b128 v[2:5], v14
	ds_read_b128 v[6:9], v14 offset:4608
	ds_read_b128 v[158:161], v14 offset:32
	ds_read_b128 v[162:165], v14 offset:4640
	ds_read_b128 v[166:169], v14 offset:64
	ds_read_b128 v[194:197], v14 offset:4672
	ds_read_b128 v[198:201], v14 offset:96
	ds_read_b128 v[202:205], v14 offset:4704
	ds_read_b128 v[234:237], v129
	ds_read_b128 v[238:241], v129 offset:4608
	ds_read_b128 v[242:245], v129 offset:32
	v_exp_f32_e32 v32, v32
	v_exp_f32_e32 v33, v33
	v_exp_f32_e32 v34, v34
	v_exp_f32_e32 v35, v35
	v_exp_f32_e32 v36, v36
	v_add_f32_e32 v10, 0, v32
	v_exp_f32_e32 v37, v37
	v_add_f32_e32 v10, v10, v33
	v_exp_f32_e32 v38, v38
	v_add_f32_e32 v10, v10, v34
	v_exp_f32_e32 v39, v39
	v_add_f32_e32 v10, v10, v35
	v_exp_f32_e32 v40, v40
	v_add_f32_e32 v10, v10, v36
	v_exp_f32_e32 v41, v41
	v_add_f32_e32 v10, v10, v37
	v_exp_f32_e32 v42, v42
	v_add_f32_e32 v10, v10, v38
	v_exp_f32_e32 v43, v43
	v_add_f32_e32 v10, v10, v39
	v_exp_f32_e32 v44, v44
	v_add_f32_e32 v10, v10, v40
	v_exp_f32_e32 v45, v45
	v_add_f32_e32 v10, v10, v41
	v_exp_f32_e32 v46, v46
	v_add_f32_e32 v10, v10, v42
	v_exp_f32_e32 v47, v47
	v_add_f32_e32 v10, v10, v43
	v_add_f32_e32 v10, v10, v44
	v_add_f32_e32 v10, v10, v45
	v_add_f32_e32 v10, v10, v46
	v_add_f32_e32 v10, v10, v47
	v_cvt_pk_bf16_f32 v108, v32, v33
	v_cvt_pk_bf16_f32 v109, v34, v35
	v_cvt_pk_bf16_f32 v110, v36, v37
	v_cvt_pk_bf16_f32 v111, v38, v39
	v_cvt_pk_bf16_f32 v116, v40, v41
	v_cvt_pk_bf16_f32 v117, v42, v43
	v_cvt_pk_bf16_f32 v118, v44, v45
	v_cvt_pk_bf16_f32 v119, v46, v47
	v_mov_b64_e32 v[32:33], v[246:247]
	v_mov_b64_e32 v[34:35], v[246:247]
	v_mov_b64_e32 v[36:37], v[246:247]
	v_mov_b64_e32 v[38:39], v[246:247]
	v_mov_b64_e32 v[40:41], v[246:247]
	v_mov_b64_e32 v[42:43], v[246:247]
	v_mov_b64_e32 v[44:45], v[246:247]
	v_mov_b64_e32 v[46:47], v[246:247]
	v_exp_f32_e32 v16, v16
	v_exp_f32_e32 v17, v17
	v_exp_f32_e32 v18, v18
	v_exp_f32_e32 v19, v19
	v_exp_f32_e32 v20, v20
	v_add_f32_e32 v11, 0, v16
	v_exp_f32_e32 v21, v21
	v_add_f32_e32 v11, v11, v17
	v_exp_f32_e32 v22, v22
	v_add_f32_e32 v11, v11, v18
	v_exp_f32_e32 v23, v23
	v_add_f32_e32 v11, v11, v19
	v_exp_f32_e32 v24, v24
	v_add_f32_e32 v11, v11, v20
	v_exp_f32_e32 v25, v25
	v_add_f32_e32 v11, v11, v21
	v_exp_f32_e32 v26, v26
	v_add_f32_e32 v11, v11, v22
	v_exp_f32_e32 v27, v27
	v_add_f32_e32 v11, v11, v23
	v_exp_f32_e32 v28, v28
	v_add_f32_e32 v11, v11, v24
	v_exp_f32_e32 v29, v29
	v_add_f32_e32 v11, v11, v25
	v_exp_f32_e32 v30, v30
	v_add_f32_e32 v11, v11, v26
	v_exp_f32_e32 v31, v31
	v_add_f32_e32 v11, v11, v27
	v_add_f32_e32 v11, v11, v28
	v_add_f32_e32 v11, v11, v29
	v_add_f32_e32 v11, v11, v30
	v_add_f32_e32 v11, v11, v31
	v_cvt_pk_bf16_f32 v104, v16, v17
	v_cvt_pk_bf16_f32 v105, v18, v19
	v_cvt_pk_bf16_f32 v106, v20, v21
	v_cvt_pk_bf16_f32 v107, v22, v23
	v_cvt_pk_bf16_f32 v112, v24, v25
	v_cvt_pk_bf16_f32 v113, v26, v27
	v_cvt_pk_bf16_f32 v114, v28, v29
	v_cvt_pk_bf16_f32 v115, v30, v31
	v_mov_b64_e32 v[16:17], v[246:247]
	v_mov_b64_e32 v[18:19], v[246:247]
	v_mov_b64_e32 v[20:21], v[246:247]
	v_mov_b64_e32 v[22:23], v[246:247]
	v_mov_b64_e32 v[24:25], v[246:247]
	v_mov_b64_e32 v[26:27], v[246:247]
	v_mov_b64_e32 v[28:29], v[246:247]
	v_mov_b64_e32 v[30:31], v[246:247]
	v_add_f32_e32 v1, v10, v11
	v_add_f32_e32 v131, v131, v1
	s_barrier
; #define ATT_BAR() do { asm volatile("s_waitcnt lgkmcnt(0)" ::: "memory"); __builtin_amdgcn_s_barrier(); asm volatile("" ::: "memory"); } while (0)
; #define ATT_LD(j, KR, VR) do { KR = *(const u32x4*)(Kb + (kg0 + (long)(j) * 64 * D)); VR = *(const u32x4*)(Vt + (vg0 + (long)(j) * 64)); } while (0)
; #define ATT_ST(j, KR, VR) do { LAS unsigned char* kd_ = lds + ATT_KS + ((j) & 3) * KS_TILE + lr * KS_PITCH + pc * 16; LAS unsigned char* vd_ = lds + ATT_VS + ((j) & 3) * VS_TILE + lr * VS_PITCH + (pc >> 1) * 32 + (pc & 1) * 8;     \
;         *(LAS u32x4*)kd_ = KR; *(LAS u32x2*)vd_ = (u32x2){VR.x, VR.y}; *(LAS u32x2*)(vd_ + 16) = (u32x2){VR.z, VR.w}; } while (0)
; __device__ __forceinline__ void attn_phase(LAS unsigned char* lds, const bf16_t* Q, const bf16_t* Kb, const bf16_t* Vt, bf16_t* O, const float* relb, const float* qn, const float* kn, int vcu, int G) {
;     ...
;         for (int g = jlo; g <= 12; ++g) {
;             const int bcg = g - cw, bcp = bcg - 1;
;             const bool actg = (g <= 11) && bcg >= 0 && bcg <= 8, actp = (g - 1 >= jlo) && bcp >= 0 && bcp <= 8;
;             if (actg) ATT_QK(g, bcg, sc0, sc1);
;             if (actp) ATT_PV(g - 1, pw);
;             ATT_BAR();
;             if (g + 2 <= 11) ATT_ST(g + 2, kreg, vreg);
;             if (g + 3 <= 11) ATT_LD(g + 3, kreg, vreg);
;             if (actg) ATT_SM(sc0, sc1, pw);
;             ATT_BAR();
;         }
	s_waitcnt lgkmcnt(0)
	v_mfma_f32_32x32x16_bf16 v[64:79], v[234:237], v[104:107], v[64:79]
	v_mfma_f32_32x32x16_bf16 v[48:63], v[238:241], v[104:107], v[48:63]
	v_mfma_f32_32x32x16_bf16 v[64:79], v[242:245], v[112:115], v[64:79]
	s_waitcnt lgkmcnt(0)
	v_mfma_f32_32x32x16_bf16 v[16:31], v[2:5], v[80:83], v[16:31]
	ds_read_b128 v[2:5], v129 offset:4640
	v_mfma_f32_32x32x16_bf16 v[32:47], v[6:9], v[80:83], v[32:47]
	ds_read_b128 v[6:9], v129 offset:64
	v_mfma_f32_32x32x16_bf16 v[16:31], v[158:161], v[84:87], v[16:31]
	ds_read_b128 v[158:161], v129 offset:4672
	v_mfma_f32_32x32x16_bf16 v[32:47], v[162:165], v[84:87], v[32:47]
	ds_read_b128 v[162:165], v129 offset:96
	v_mfma_f32_32x32x16_bf16 v[16:31], v[166:169], v[88:91], v[16:31]
	ds_read_b128 v[166:169], v129 offset:4704
	v_mfma_f32_32x32x16_bf16 v[32:47], v[194:197], v[88:91], v[32:47]
	v_mfma_f32_32x32x16_bf16 v[16:31], v[198:201], v[92:95], v[16:31]
	v_mfma_f32_32x32x16_bf16 v[32:47], v[202:205], v[92:95], v[32:47]
	s_waitcnt lgkmcnt(4)
	v_mfma_f32_32x32x16_bf16 v[48:63], v[2:5], v[112:115], v[48:63]
	s_waitcnt lgkmcnt(3)
	v_mfma_f32_32x32x16_bf16 v[64:79], v[6:9], v[108:111], v[64:79]
	s_waitcnt lgkmcnt(2)
	v_mfma_f32_32x32x16_bf16 v[48:63], v[158:161], v[108:111], v[48:63]
	s_waitcnt lgkmcnt(1)
	v_mfma_f32_32x32x16_bf16 v[64:79], v[162:165], v[116:119], v[64:79]
	s_waitcnt lgkmcnt(0)
	v_mfma_f32_32x32x16_bf16 v[48:63], v[166:169], v[116:119], v[48:63]
	s_waitcnt lgkmcnt(0)
	s_barrier
	s_waitcnt vmcnt(4)
	ds_write_b128 v151, v[218:221] offset:9216
	v_add_u32_e32 v1, 0x9000, v152
	ds_write2_b64 v1, v[100:101], v[102:103] offset1:2
	global_load_dwordx4 v[218:221], v[140:141], off
	v_lshl_add_u64 v[140:141], v[140:141], 0, s[44:45]
	global_load_dwordx4 v[100:103], v[138:139], off
	v_lshl_add_u64 v[138:139], v[138:139], 0, s[62:63]
	ds_read_b128 v[2:5], v15
	ds_read_b128 v[6:9], v15 offset:4608
	ds_read_b128 v[158:161], v15 offset:32
	ds_read_b128 v[162:165], v15 offset:4640
	ds_read_b128 v[166:169], v15 offset:64
	ds_read_b128 v[194:197], v15 offset:4672
	ds_read_b128 v[198:201], v15 offset:96
	ds_read_b128 v[202:205], v15 offset:4704
	ds_read_b128 v[234:237], v157
	ds_read_b128 v[238:241], v157 offset:4608
	ds_read_b128 v[242:245], v157 offset:32
	v_exp_f32_e32 v32, v32
	v_exp_f32_e32 v33, v33
	v_exp_f32_e32 v34, v34
	v_exp_f32_e32 v35, v35
	v_exp_f32_e32 v36, v36
	v_add_f32_e32 v10, 0, v32
	v_exp_f32_e32 v37, v37
	v_add_f32_e32 v10, v10, v33
	v_exp_f32_e32 v38, v38
	v_add_f32_e32 v10, v10, v34
	v_exp_f32_e32 v39, v39
	v_add_f32_e32 v10, v10, v35
	v_exp_f32_e32 v40, v40
	v_add_f32_e32 v10, v10, v36
	v_exp_f32_e32 v41, v41
	v_add_f32_e32 v10, v10, v37
	v_exp_f32_e32 v42, v42
	v_add_f32_e32 v10, v10, v38
	v_exp_f32_e32 v43, v43
	v_add_f32_e32 v10, v10, v39
	v_exp_f32_e32 v44, v44
	v_add_f32_e32 v10, v10, v40
	v_exp_f32_e32 v45, v45
	v_add_f32_e32 v10, v10, v41
	v_exp_f32_e32 v46, v46
	v_add_f32_e32 v10, v10, v42
	v_exp_f32_e32 v47, v47
	v_add_f32_e32 v10, v10, v43
	v_add_f32_e32 v10, v10, v44
	v_add_f32_e32 v10, v10, v45
	v_add_f32_e32 v10, v10, v46
	v_add_f32_e32 v10, v10, v47
	v_cvt_pk_bf16_f32 v108, v32, v33
	v_cvt_pk_bf16_f32 v109, v34, v35
	v_cvt_pk_bf16_f32 v110, v36, v37
	v_cvt_pk_bf16_f32 v111, v38, v39
	v_cvt_pk_bf16_f32 v116, v40, v41
	v_cvt_pk_bf16_f32 v117, v42, v43
	v_cvt_pk_bf16_f32 v118, v44, v45
	v_cvt_pk_bf16_f32 v119, v46, v47
	v_mov_b64_e32 v[32:33], v[246:247]
	v_mov_b64_e32 v[34:35], v[246:247]
	v_mov_b64_e32 v[36:37], v[246:247]
	v_mov_b64_e32 v[38:39], v[246:247]
	v_mov_b64_e32 v[40:41], v[246:247]
	v_mov_b64_e32 v[42:43], v[246:247]
	v_mov_b64_e32 v[44:45], v[246:247]
	v_mov_b64_e32 v[46:47], v[246:247]
	v_exp_f32_e32 v16, v16
	v_exp_f32_e32 v17, v17
	v_exp_f32_e32 v18, v18
	v_exp_f32_e32 v19, v19
	v_exp_f32_e32 v20, v20
	v_add_f32_e32 v11, 0, v16
	v_exp_f32_e32 v21, v21
	v_add_f32_e32 v11, v11, v17
	v_exp_f32_e32 v22, v22
	v_add_f32_e32 v11, v11, v18
	v_exp_f32_e32 v23, v23
	v_add_f32_e32 v11, v11, v19
	v_exp_f32_e32 v24, v24
	v_add_f32_e32 v11, v11, v20
	v_exp_f32_e32 v25, v25
	v_add_f32_e32 v11, v11, v21
	v_exp_f32_e32 v26, v26
	v_add_f32_e32 v11, v11, v22
	v_exp_f32_e32 v27, v27
	v_add_f32_e32 v11, v11, v23
	v_exp_f32_e32 v28, v28
	v_add_f32_e32 v11, v11, v24
	v_exp_f32_e32 v29, v29
	v_add_f32_e32 v11, v11, v25
	v_exp_f32_e32 v30, v30
	v_add_f32_e32 v11, v11, v26
	v_exp_f32_e32 v31, v31
	v_add_f32_e32 v11, v11, v27
	v_add_f32_e32 v11, v11, v28
	v_add_f32_e32 v11, v11, v29
	v_add_f32_e32 v11, v11, v30
	v_add_f32_e32 v11, v11, v31
	v_cvt_pk_bf16_f32 v104, v16, v17
	v_cvt_pk_bf16_f32 v105, v18, v19
	v_cvt_pk_bf16_f32 v106, v20, v21
	v_cvt_pk_bf16_f32 v107, v22, v23
	v_cvt_pk_bf16_f32 v112, v24, v25
	v_cvt_pk_bf16_f32 v113, v26, v27
	v_cvt_pk_bf16_f32 v114, v28, v29
	v_cvt_pk_bf16_f32 v115, v30, v31
	v_mov_b64_e32 v[16:17], v[246:247]
	v_mov_b64_e32 v[18:19], v[246:247]
	v_mov_b64_e32 v[20:21], v[246:247]
	v_mov_b64_e32 v[22:23], v[246:247]
	v_mov_b64_e32 v[24:25], v[246:247]
	v_mov_b64_e32 v[26:27], v[246:247]
	v_mov_b64_e32 v[28:29], v[246:247]
	v_mov_b64_e32 v[30:31], v[246:247]
	v_add_f32_e32 v1, v10, v11
	v_add_f32_e32 v131, v131, v1
	s_barrier
; #define ATT_BAR() do { asm volatile("s_waitcnt lgkmcnt(0)" ::: "memory"); __builtin_amdgcn_s_barrier(); asm volatile("" ::: "memory"); } while (0)
; #define ATT_LD(j, KR, VR) do { KR = *(const u32x4*)(Kb + (kg0 + (long)(j) * 64 * D)); VR = *(const u32x4*)(Vt + (vg0 + (long)(j) * 64)); } while (0)
; #define ATT_ST(j, KR, VR) do { LAS unsigned char* kd_ = lds + ATT_KS + ((j) & 3) * KS_TILE + lr * KS_PITCH + pc * 16; LAS unsigned char* vd_ = lds + ATT_VS + ((j) & 3) * VS_TILE + lr * VS_PITCH + (pc >> 1) * 32 + (pc & 1) * 8;     \
;         *(LAS u32x4*)kd_ = KR; *(LAS u32x2*)vd_ = (u32x2){VR.x, VR.y}; *(LAS u32x2*)(vd_ + 16) = (u32x2){VR.z, VR.w}; } while (0)
; __device__ __forceinline__ void attn_phase(LAS unsigned char* lds, const bf16_t* Q, const bf16_t* Kb, const bf16_t* Vt, bf16_t* O, const float* relb, const float* qn, const float* kn, int vcu, int G) {
;     ...
;         for (int g = jlo; g <= 12; ++g) {
;             const int bcg = g - cw, bcp = bcg - 1;
;             const bool actg = (g <= 11) && bcg >= 0 && bcg <= 8, actp = (g - 1 >= jlo) && bcp >= 0 && bcp <= 8;
;             if (actg) ATT_QK(g, bcg, sc0, sc1);
;             if (actp) ATT_PV(g - 1, pw);
;             ATT_BAR();
;             if (g + 2 <= 11) ATT_ST(g + 2, kreg, vreg);
;             if (g + 3 <= 11) ATT_LD(g + 3, kreg, vreg);
;             if (actg) ATT_SM(sc0, sc1, pw);
;             ATT_BAR();
;         }
	s_waitcnt lgkmcnt(0)
	v_mfma_f32_32x32x16_bf16 v[64:79], v[234:237], v[104:107], v[64:79]
	v_mfma_f32_32x32x16_bf16 v[48:63], v[238:241], v[104:107], v[48:63]
	v_mfma_f32_32x32x16_bf16 v[64:79], v[242:245], v[112:115], v[64:79]
	s_waitcnt lgkmcnt(0)
	v_mfma_f32_32x32x16_bf16 v[16:31], v[2:5], v[80:83], v[16:31]
	ds_read_b128 v[2:5], v157 offset:4640
	v_mfma_f32_32x32x16_bf16 v[32:47], v[6:9], v[80:83], v[32:47]
	ds_read_b128 v[6:9], v157 offset:64
	v_mfma_f32_32x32x16_bf16 v[16:31], v[158:161], v[84:87], v[16:31]
	ds_read_b128 v[158:161], v157 offset:4672
	v_mfma_f32_32x32x16_bf16 v[32:47], v[162:165], v[84:87], v[32:47]
	ds_read_b128 v[162:165], v157 offset:96
	v_mfma_f32_32x32x16_bf16 v[16:31], v[166:169], v[88:91], v[16:31]
	ds_read_b128 v[166:169], v157 offset:4704
	v_mfma_f32_32x32x16_bf16 v[32:47], v[194:197], v[88:91], v[32:47]
	v_mfma_f32_32x32x16_bf16 v[16:31], v[198:201], v[92:95], v[16:31]
	v_mfma_f32_32x32x16_bf16 v[32:47], v[202:205], v[92:95], v[32:47]
	s_waitcnt lgkmcnt(4)
	v_mfma_f32_32x32x16_bf16 v[48:63], v[2:5], v[112:115], v[48:63]
	s_waitcnt lgkmcnt(3)
	v_mfma_f32_32x32x16_bf16 v[64:79], v[6:9], v[108:111], v[64:79]
	s_waitcnt lgkmcnt(2)
	v_mfma_f32_32x32x16_bf16 v[48:63], v[158:161], v[108:111], v[48:63]
	s_waitcnt lgkmcnt(1)
	v_mfma_f32_32x32x16_bf16 v[64:79], v[162:165], v[116:119], v[64:79]
	s_waitcnt lgkmcnt(0)
	v_mfma_f32_32x32x16_bf16 v[48:63], v[166:169], v[116:119], v[48:63]
	s_waitcnt lgkmcnt(0)
	s_barrier
	s_waitcnt vmcnt(4)
	ds_write_b128 v151, v[226:229] offset:18432
	v_add_u32_e32 v1, 0xb400, v152
	ds_write2_b64 v1, v[222:223], v[224:225] offset1:2
	global_load_dwordx4 v[226:229], v[140:141], off
	v_lshl_add_u64 v[140:141], v[140:141], 0, s[44:45]
	global_load_dwordx4 v[222:225], v[138:139], off
	v_lshl_add_u64 v[138:139], v[138:139], 0, s[62:63]
	ds_read_b128 v[2:5], v126
	ds_read_b128 v[6:9], v126 offset:4608
	ds_read_b128 v[158:161], v126 offset:32
	ds_read_b128 v[162:165], v126 offset:4640
	ds_read_b128 v[166:169], v126 offset:64
	ds_read_b128 v[194:197], v126 offset:4672
	ds_read_b128 v[198:201], v126 offset:96
	ds_read_b128 v[202:205], v126 offset:4704
	ds_read_b128 v[234:237], v217
	ds_read_b128 v[238:241], v217 offset:4608
	ds_read_b128 v[242:245], v217 offset:32
	v_exp_f32_e32 v32, v32
	v_exp_f32_e32 v33, v33
	v_exp_f32_e32 v34, v34
	v_exp_f32_e32 v35, v35
	v_exp_f32_e32 v36, v36
	v_add_f32_e32 v10, 0, v32
	v_exp_f32_e32 v37, v37
	v_add_f32_e32 v10, v10, v33
	v_exp_f32_e32 v38, v38
	v_add_f32_e32 v10, v10, v34
	v_exp_f32_e32 v39, v39
	v_add_f32_e32 v10, v10, v35
	v_exp_f32_e32 v40, v40
	v_add_f32_e32 v10, v10, v36
	v_exp_f32_e32 v41, v41
	v_add_f32_e32 v10, v10, v37
	v_exp_f32_e32 v42, v42
	v_add_f32_e32 v10, v10, v38
	v_exp_f32_e32 v43, v43
	v_add_f32_e32 v10, v10, v39
	v_exp_f32_e32 v44, v44
	v_add_f32_e32 v10, v10, v40
	v_exp_f32_e32 v45, v45
	v_add_f32_e32 v10, v10, v41
	v_exp_f32_e32 v46, v46
	v_add_f32_e32 v10, v10, v42
	v_exp_f32_e32 v47, v47
	v_add_f32_e32 v10, v10, v43
	v_add_f32_e32 v10, v10, v44
	v_add_f32_e32 v10, v10, v45
	v_add_f32_e32 v10, v10, v46
	v_add_f32_e32 v10, v10, v47
	v_cvt_pk_bf16_f32 v108, v32, v33
	v_cvt_pk_bf16_f32 v109, v34, v35
	v_cvt_pk_bf16_f32 v110, v36, v37
	v_cvt_pk_bf16_f32 v111, v38, v39
	v_cvt_pk_bf16_f32 v116, v40, v41
	v_cvt_pk_bf16_f32 v117, v42, v43
	v_cvt_pk_bf16_f32 v118, v44, v45
	v_cvt_pk_bf16_f32 v119, v46, v47
	s_waitcnt lgkmcnt(11)
	ds_read_b128 v[32:35], v133 offset:1152
	ds_read_b128 v[36:39], v133 offset:1184
	ds_read_b128 v[40:43], v133 offset:1216
	ds_read_b128 v[44:47], v133 offset:1248
	v_exp_f32_e32 v16, v16
	v_exp_f32_e32 v17, v17
	v_exp_f32_e32 v18, v18
	v_exp_f32_e32 v19, v19
	v_exp_f32_e32 v20, v20
	v_add_f32_e32 v11, 0, v16
	v_exp_f32_e32 v21, v21
	v_add_f32_e32 v11, v11, v17
	v_exp_f32_e32 v22, v22
	v_add_f32_e32 v11, v11, v18
	v_exp_f32_e32 v23, v23
	v_add_f32_e32 v11, v11, v19
	v_exp_f32_e32 v24, v24
	v_add_f32_e32 v11, v11, v20
	v_exp_f32_e32 v25, v25
	v_add_f32_e32 v11, v11, v21
	v_exp_f32_e32 v26, v26
	v_add_f32_e32 v11, v11, v22
	v_exp_f32_e32 v27, v27
	v_add_f32_e32 v11, v11, v23
	v_exp_f32_e32 v28, v28
	v_add_f32_e32 v11, v11, v24
	v_exp_f32_e32 v29, v29
	v_add_f32_e32 v11, v11, v25
	v_exp_f32_e32 v30, v30
	v_add_f32_e32 v11, v11, v26
	v_exp_f32_e32 v31, v31
	v_add_f32_e32 v11, v11, v27
	v_add_f32_e32 v11, v11, v28
	v_add_f32_e32 v11, v11, v29
	v_add_f32_e32 v11, v11, v30
	v_add_f32_e32 v11, v11, v31
	v_cvt_pk_bf16_f32 v104, v16, v17
	v_cvt_pk_bf16_f32 v105, v18, v19
	v_cvt_pk_bf16_f32 v106, v20, v21
	v_cvt_pk_bf16_f32 v107, v22, v23
	v_cvt_pk_bf16_f32 v112, v24, v25
	v_cvt_pk_bf16_f32 v113, v26, v27
	v_cvt_pk_bf16_f32 v114, v28, v29
	v_cvt_pk_bf16_f32 v115, v30, v31
	s_waitcnt lgkmcnt(8)
	ds_read_b128 v[16:19], v133 offset:1024
	ds_read_b128 v[20:23], v133 offset:1056
	ds_read_b128 v[24:27], v133 offset:1088
	ds_read_b128 v[28:31], v133 offset:1120
	v_add_f32_e32 v1, v10, v11
	v_add_f32_e32 v131, v131, v1
	s_barrier
; #define ATT_BAR() do { asm volatile("s_waitcnt lgkmcnt(0)" ::: "memory"); __builtin_amdgcn_s_barrier(); asm volatile("" ::: "memory"); } while (0)
; #define ATT_LD(j, KR, VR) do { KR = *(const u32x4*)(Kb + (kg0 + (long)(j) * 64 * D)); VR = *(const u32x4*)(Vt + (vg0 + (long)(j) * 64)); } while (0)
; #define ATT_ST(j, KR, VR) do { LAS unsigned char* kd_ = lds + ATT_KS + ((j) & 3) * KS_TILE + lr * KS_PITCH + pc * 16; LAS unsigned char* vd_ = lds + ATT_VS + ((j) & 3) * VS_TILE + lr * VS_PITCH + (pc >> 1) * 32 + (pc & 1) * 8;     \
;         *(LAS u32x4*)kd_ = KR; *(LAS u32x2*)vd_ = (u32x2){VR.x, VR.y}; *(LAS u32x2*)(vd_ + 16) = (u32x2){VR.z, VR.w}; } while (0)
; __device__ __forceinline__ void attn_phase(LAS unsigned char* lds, const bf16_t* Q, const bf16_t* Kb, const bf16_t* Vt, bf16_t* O, const float* relb, const float* qn, const float* kn, int vcu, int G) {
;     ...
;         for (int g = jlo; g <= 12; ++g) {
;             const int bcg = g - cw, bcp = bcg - 1;
;             const bool actg = (g <= 11) && bcg >= 0 && bcg <= 8, actp = (g - 1 >= jlo) && bcp >= 0 && bcp <= 8;
;             if (actg) ATT_QK(g, bcg, sc0, sc1);
;             if (actp) ATT_PV(g - 1, pw);
;             ATT_BAR();
;             if (g + 2 <= 11) ATT_ST(g + 2, kreg, vreg);
;             if (g + 3 <= 11) ATT_LD(g + 3, kreg, vreg);
;             if (actg) ATT_SM(sc0, sc1, pw);
;             ATT_BAR();
;         }
	s_waitcnt lgkmcnt(8)
	v_mfma_f32_32x32x16_bf16 v[64:79], v[234:237], v[104:107], v[64:79]
	v_mfma_f32_32x32x16_bf16 v[48:63], v[238:241], v[104:107], v[48:63]
	v_mfma_f32_32x32x16_bf16 v[64:79], v[242:245], v[112:115], v[64:79]
	s_waitcnt lgkmcnt(0)
	v_mfma_f32_32x32x16_bf16 v[16:31], v[2:5], v[80:83], v[16:31]
	ds_read_b128 v[2:5], v217 offset:4640
	v_mfma_f32_32x32x16_bf16 v[32:47], v[6:9], v[80:83], v[32:47]
	ds_read_b128 v[6:9], v217 offset:64
	v_mfma_f32_32x32x16_bf16 v[16:31], v[158:161], v[84:87], v[16:31]
	ds_read_b128 v[158:161], v217 offset:4672
	v_mfma_f32_32x32x16_bf16 v[32:47], v[162:165], v[84:87], v[32:47]
	ds_read_b128 v[162:165], v217 offset:96
	v_mfma_f32_32x32x16_bf16 v[16:31], v[166:169], v[88:91], v[16:31]
	ds_read_b128 v[166:169], v217 offset:4704
	v_mfma_f32_32x32x16_bf16 v[32:47], v[194:197], v[88:91], v[32:47]
	v_mfma_f32_32x32x16_bf16 v[16:31], v[198:201], v[92:95], v[16:31]
	v_mfma_f32_32x32x16_bf16 v[32:47], v[202:205], v[92:95], v[32:47]
	s_waitcnt lgkmcnt(4)
	v_mfma_f32_32x32x16_bf16 v[48:63], v[2:5], v[112:115], v[48:63]
	s_waitcnt lgkmcnt(3)
	v_mfma_f32_32x32x16_bf16 v[64:79], v[6:9], v[108:111], v[64:79]
	s_waitcnt lgkmcnt(2)
	v_mfma_f32_32x32x16_bf16 v[48:63], v[158:161], v[108:111], v[48:63]
	s_waitcnt lgkmcnt(1)
	v_mfma_f32_32x32x16_bf16 v[64:79], v[162:165], v[116:119], v[64:79]
	s_waitcnt lgkmcnt(0)
	v_mfma_f32_32x32x16_bf16 v[48:63], v[166:169], v[116:119], v[48:63]
	s_waitcnt lgkmcnt(0)
	s_barrier
	s_waitcnt vmcnt(4)
	ds_write_b128 v151, v[96:99] offset:27648
	v_add_u32_e32 v1, 0xd800, v152
	ds_write2_b64 v1, v[230:231], v[232:233] offset1:2
	global_load_dwordx4 v[230:233], v[138:139], off
	v_lshl_add_u64 v[138:139], v[138:139], 0, s[62:63]
	ds_read_b128 v[2:5], v127
	ds_read_b128 v[6:9], v127 offset:4608
	ds_read_b128 v[158:161], v127 offset:32
	ds_read_b128 v[162:165], v127 offset:4640
	ds_read_b128 v[166:169], v127 offset:64
	ds_read_b128 v[194:197], v127 offset:4672
	ds_read_b128 v[198:201], v127 offset:96
	ds_read_b128 v[202:205], v127 offset:4704
	ds_read_b128 v[234:237], v253
	ds_read_b128 v[238:241], v253 offset:4608
	ds_read_b128 v[242:245], v253 offset:32
	v_exp_f32_e32 v32, v32
	v_exp_f32_e32 v33, v33
	v_exp_f32_e32 v34, v34
	v_exp_f32_e32 v35, v35
	v_exp_f32_e32 v36, v36
	v_add_f32_e32 v10, 0, v32
	v_exp_f32_e32 v37, v37
	v_add_f32_e32 v10, v10, v33
	v_exp_f32_e32 v38, v38
	v_add_f32_e32 v10, v10, v34
	v_exp_f32_e32 v39, v39
	v_add_f32_e32 v10, v10, v35
	v_exp_f32_e32 v40, v40
	v_add_f32_e32 v10, v10, v36
	v_exp_f32_e32 v41, v41
	v_add_f32_e32 v10, v10, v37
	v_exp_f32_e32 v42, v42
	v_add_f32_e32 v10, v10, v38
	v_exp_f32_e32 v43, v43
	v_add_f32_e32 v10, v10, v39
	v_exp_f32_e32 v44, v44
	v_add_f32_e32 v10, v10, v40
	v_exp_f32_e32 v45, v45
	v_add_f32_e32 v10, v10, v41
	v_exp_f32_e32 v46, v46
	v_add_f32_e32 v10, v10, v42
	v_exp_f32_e32 v47, v47
	v_add_f32_e32 v10, v10, v43
	v_add_f32_e32 v10, v10, v44
	v_add_f32_e32 v10, v10, v45
	v_add_f32_e32 v10, v10, v46
	v_add_f32_e32 v10, v10, v47
	v_cvt_pk_bf16_f32 v108, v32, v33
	v_cvt_pk_bf16_f32 v109, v34, v35
	v_cvt_pk_bf16_f32 v110, v36, v37
	v_cvt_pk_bf16_f32 v111, v38, v39
	v_cvt_pk_bf16_f32 v116, v40, v41
	v_cvt_pk_bf16_f32 v117, v42, v43
	v_cvt_pk_bf16_f32 v118, v44, v45
	v_cvt_pk_bf16_f32 v119, v46, v47
	s_waitcnt lgkmcnt(11)
	ds_read_b128 v[32:35], v133 offset:1408
	ds_read_b128 v[36:39], v133 offset:1440
	ds_read_b128 v[40:43], v133 offset:1472
	ds_read_b128 v[44:47], v133 offset:1504
	v_exp_f32_e32 v16, v16
	v_exp_f32_e32 v17, v17
	v_exp_f32_e32 v18, v18
	v_exp_f32_e32 v19, v19
	v_exp_f32_e32 v20, v20
	v_add_f32_e32 v11, 0, v16
	v_exp_f32_e32 v21, v21
	v_add_f32_e32 v11, v11, v17
	v_exp_f32_e32 v22, v22
	v_add_f32_e32 v11, v11, v18
	v_exp_f32_e32 v23, v23
	v_add_f32_e32 v11, v11, v19
	v_exp_f32_e32 v24, v24
	v_add_f32_e32 v11, v11, v20
	v_exp_f32_e32 v25, v25
	v_add_f32_e32 v11, v11, v21
	v_exp_f32_e32 v26, v26
	v_add_f32_e32 v11, v11, v22
	v_exp_f32_e32 v27, v27
	v_add_f32_e32 v11, v11, v23
	v_exp_f32_e32 v28, v28
	v_add_f32_e32 v11, v11, v24
	v_exp_f32_e32 v29, v29
	v_add_f32_e32 v11, v11, v25
	v_exp_f32_e32 v30, v30
	v_add_f32_e32 v11, v11, v26
	v_exp_f32_e32 v31, v31
	v_add_f32_e32 v11, v11, v27
	v_add_f32_e32 v11, v11, v28
	v_add_f32_e32 v11, v11, v29
	v_add_f32_e32 v11, v11, v30
	v_add_f32_e32 v11, v11, v31
	v_cvt_pk_bf16_f32 v104, v16, v17
	v_cvt_pk_bf16_f32 v105, v18, v19
	v_cvt_pk_bf16_f32 v106, v20, v21
	v_cvt_pk_bf16_f32 v107, v22, v23
	v_cvt_pk_bf16_f32 v112, v24, v25
	v_cvt_pk_bf16_f32 v113, v26, v27
	v_cvt_pk_bf16_f32 v114, v28, v29
	v_cvt_pk_bf16_f32 v115, v30, v31
	s_waitcnt lgkmcnt(8)
	ds_read_b128 v[16:19], v133 offset:1280
	ds_read_b128 v[20:23], v133 offset:1312
	ds_read_b128 v[24:27], v133 offset:1344
	ds_read_b128 v[28:31], v133 offset:1376
	v_add_f32_e32 v1, v10, v11
	v_add_f32_e32 v131, v131, v1
	s_barrier
	s_waitcnt lgkmcnt(8)
	v_mfma_f32_32x32x16_bf16 v[64:79], v[234:237], v[104:107], v[64:79]
	v_mfma_f32_32x32x16_bf16 v[48:63], v[238:241], v[104:107], v[48:63]
	v_mfma_f32_32x32x16_bf16 v[64:79], v[242:245], v[112:115], v[64:79]
	s_waitcnt lgkmcnt(0)
	v_mfma_f32_32x32x16_bf16 v[16:31], v[2:5], v[80:83], v[16:31]
	ds_read_b128 v[2:5], v253 offset:4640
	v_mfma_f32_32x32x16_bf16 v[32:47], v[6:9], v[80:83], v[32:47]
	ds_read_b128 v[6:9], v253 offset:64
	v_mfma_f32_32x32x16_bf16 v[16:31], v[158:161], v[84:87], v[16:31]
	ds_read_b128 v[158:161], v253 offset:4672
	v_mfma_f32_32x32x16_bf16 v[32:47], v[162:165], v[84:87], v[32:47]
	ds_read_b128 v[162:165], v253 offset:96
	v_mfma_f32_32x32x16_bf16 v[16:31], v[166:169], v[88:91], v[16:31]
	ds_read_b128 v[166:169], v253 offset:4704
	v_mfma_f32_32x32x16_bf16 v[32:47], v[194:197], v[88:91], v[32:47]
	v_mfma_f32_32x32x16_bf16 v[16:31], v[198:201], v[92:95], v[16:31]
	v_mfma_f32_32x32x16_bf16 v[32:47], v[202:205], v[92:95], v[32:47]
	s_waitcnt lgkmcnt(4)
	v_mfma_f32_32x32x16_bf16 v[48:63], v[2:5], v[112:115], v[48:63]
	s_waitcnt lgkmcnt(3)
	v_mfma_f32_32x32x16_bf16 v[64:79], v[6:9], v[108:111], v[64:79]
	s_waitcnt lgkmcnt(2)
	v_mfma_f32_32x32x16_bf16 v[48:63], v[158:161], v[108:111], v[48:63]
	s_waitcnt lgkmcnt(1)
	v_mfma_f32_32x32x16_bf16 v[64:79], v[162:165], v[116:119], v[64:79]
	s_waitcnt lgkmcnt(0)
	v_mfma_f32_32x32x16_bf16 v[48:63], v[166:169], v[116:119], v[48:63]
	s_waitcnt lgkmcnt(0)
	s_barrier
; #define ATT_BAR() do { asm volatile("s_waitcnt lgkmcnt(0)" ::: "memory"); __builtin_amdgcn_s_barrier(); asm volatile("" ::: "memory"); } while (0)
; #define ATT_LD(j, KR, VR) do { KR = *(const u32x4*)(Kb + (kg0 + (long)(j) * 64 * D)); VR = *(const u32x4*)(Vt + (vg0 + (long)(j) * 64)); } while (0)
; #define ATT_ST(j, KR, VR) do { LAS unsigned char* kd_ = lds + ATT_KS + ((j) & 3) * KS_TILE + lr * KS_PITCH + pc * 16; LAS unsigned char* vd_ = lds + ATT_VS + ((j) & 3) * VS_TILE + lr * VS_PITCH + (pc >> 1) * 32 + (pc & 1) * 8;     \
;         *(LAS u32x4*)kd_ = KR; *(LAS u32x2*)vd_ = (u32x2){VR.x, VR.y}; *(LAS u32x2*)(vd_ + 16) = (u32x2){VR.z, VR.w}; } while (0)
; __device__ __forceinline__ void attn_phase(LAS unsigned char* lds, const bf16_t* Q, const bf16_t* Kb, const bf16_t* Vt, bf16_t* O, const float* relb, const float* qn, const float* kn, int vcu, int G) {
;     ...
;         for (int g = jlo; g <= 12; ++g) {
;             const int bcg = g - cw, bcp = bcg - 1;
;             const bool actg = (g <= 11) && bcg >= 0 && bcg <= 8, actp = (g - 1 >= jlo) && bcp >= 0 && bcp <= 8;
;             if (actg) ATT_QK(g, bcg, sc0, sc1);
;             if (actp) ATT_PV(g - 1, pw);
;             ATT_BAR();
;             if (g + 2 <= 11) ATT_ST(g + 2, kreg, vreg);
;             if (g + 3 <= 11) ATT_LD(g + 3, kreg, vreg);
;             if (actg) ATT_SM(sc0, sc1, pw);
;             ATT_BAR();
;         }
	s_waitcnt vmcnt(3)
	ds_write_b128 v255, v[218:221]
	v_add_u32_e32 v1, 0xfc00, v152
	ds_write2_b64 v1, v[100:101], v[102:103] offset1:2
	ds_read_b128 v[2:5], v12
	ds_read_b128 v[6:9], v12 offset:4608
	ds_read_b128 v[158:161], v12 offset:32
	ds_read_b128 v[162:165], v12 offset:4640
	ds_read_b128 v[166:169], v12 offset:64
	ds_read_b128 v[194:197], v12 offset:4672
	ds_read_b128 v[198:201], v12 offset:96
	ds_read_b128 v[202:205], v12 offset:4704
	ds_read_b128 v[234:237], v254
	ds_read_b128 v[238:241], v254 offset:4608
	ds_read_b128 v[242:245], v254 offset:32
	v_exp_f32_e32 v32, v32
	v_exp_f32_e32 v33, v33
	v_exp_f32_e32 v34, v34
	v_exp_f32_e32 v35, v35
	v_exp_f32_e32 v36, v36
	v_add_f32_e32 v10, 0, v32
	v_exp_f32_e32 v37, v37
	v_add_f32_e32 v10, v10, v33
	v_exp_f32_e32 v38, v38
	v_add_f32_e32 v10, v10, v34
	v_exp_f32_e32 v39, v39
	v_add_f32_e32 v10, v10, v35
	v_exp_f32_e32 v40, v40
	v_add_f32_e32 v10, v10, v36
	v_exp_f32_e32 v41, v41
	v_add_f32_e32 v10, v10, v37
	v_exp_f32_e32 v42, v42
	v_add_f32_e32 v10, v10, v38
	v_exp_f32_e32 v43, v43
	v_add_f32_e32 v10, v10, v39
	v_exp_f32_e32 v44, v44
	v_add_f32_e32 v10, v10, v40
	v_exp_f32_e32 v45, v45
	v_add_f32_e32 v10, v10, v41
	v_exp_f32_e32 v46, v46
	v_add_f32_e32 v10, v10, v42
	v_exp_f32_e32 v47, v47
	v_add_f32_e32 v10, v10, v43
	v_add_f32_e32 v10, v10, v44
	v_add_f32_e32 v10, v10, v45
	v_add_f32_e32 v10, v10, v46
	v_add_f32_e32 v10, v10, v47
	v_cvt_pk_bf16_f32 v108, v32, v33
	v_cvt_pk_bf16_f32 v109, v34, v35
	v_cvt_pk_bf16_f32 v110, v36, v37
	v_cvt_pk_bf16_f32 v111, v38, v39
	v_cvt_pk_bf16_f32 v116, v40, v41
	v_cvt_pk_bf16_f32 v117, v42, v43
	v_cvt_pk_bf16_f32 v118, v44, v45
	v_cvt_pk_bf16_f32 v119, v46, v47
	s_waitcnt lgkmcnt(11)
	ds_read_b128 v[32:35], v133 offset:1664
	ds_read_b128 v[36:39], v133 offset:1696
	ds_read_b128 v[40:43], v133 offset:1728
	ds_read_b128 v[44:47], v133 offset:1760
	v_exp_f32_e32 v16, v16
	v_exp_f32_e32 v17, v17
	v_exp_f32_e32 v18, v18
	v_exp_f32_e32 v19, v19
	v_exp_f32_e32 v20, v20
	v_add_f32_e32 v11, 0, v16
	v_exp_f32_e32 v21, v21
	v_add_f32_e32 v11, v11, v17
	v_exp_f32_e32 v22, v22
	v_add_f32_e32 v11, v11, v18
	v_exp_f32_e32 v23, v23
	v_add_f32_e32 v11, v11, v19
	v_exp_f32_e32 v24, v24
	v_add_f32_e32 v11, v11, v20
	v_exp_f32_e32 v25, v25
	v_add_f32_e32 v11, v11, v21
	v_exp_f32_e32 v26, v26
	v_add_f32_e32 v11, v11, v22
	v_exp_f32_e32 v27, v27
	v_add_f32_e32 v11, v11, v23
	v_exp_f32_e32 v28, v28
	v_add_f32_e32 v11, v11, v24
	v_exp_f32_e32 v29, v29
	v_add_f32_e32 v11, v11, v25
	v_exp_f32_e32 v30, v30
	v_add_f32_e32 v11, v11, v26
	v_exp_f32_e32 v31, v31
	v_add_f32_e32 v11, v11, v27
	v_add_f32_e32 v11, v11, v28
	v_add_f32_e32 v11, v11, v29
	v_add_f32_e32 v11, v11, v30
	v_add_f32_e32 v11, v11, v31
	v_cvt_pk_bf16_f32 v104, v16, v17
	v_cvt_pk_bf16_f32 v105, v18, v19
	v_cvt_pk_bf16_f32 v106, v20, v21
	v_cvt_pk_bf16_f32 v107, v22, v23
	v_cvt_pk_bf16_f32 v112, v24, v25
	v_cvt_pk_bf16_f32 v113, v26, v27
	v_cvt_pk_bf16_f32 v114, v28, v29
	v_cvt_pk_bf16_f32 v115, v30, v31
	s_waitcnt lgkmcnt(8)
	ds_read_b128 v[16:19], v133 offset:1536
	ds_read_b128 v[20:23], v133 offset:1568
	ds_read_b128 v[24:27], v133 offset:1600
	ds_read_b128 v[28:31], v133 offset:1632
	v_add_f32_e32 v1, v10, v11
	v_add_f32_e32 v131, v131, v1
	s_barrier
	s_waitcnt lgkmcnt(8)
	v_mfma_f32_32x32x16_bf16 v[64:79], v[234:237], v[104:107], v[64:79]
	v_mfma_f32_32x32x16_bf16 v[48:63], v[238:241], v[104:107], v[48:63]
	v_mfma_f32_32x32x16_bf16 v[64:79], v[242:245], v[112:115], v[64:79]
	s_waitcnt lgkmcnt(0)
	v_mfma_f32_32x32x16_bf16 v[16:31], v[2:5], v[80:83], v[16:31]
	ds_read_b128 v[2:5], v254 offset:4640
	v_mfma_f32_32x32x16_bf16 v[32:47], v[6:9], v[80:83], v[32:47]
	ds_read_b128 v[6:9], v254 offset:64
	v_mfma_f32_32x32x16_bf16 v[16:31], v[158:161], v[84:87], v[16:31]
	ds_read_b128 v[158:161], v254 offset:4672
	v_mfma_f32_32x32x16_bf16 v[32:47], v[162:165], v[84:87], v[32:47]
	ds_read_b128 v[162:165], v254 offset:96
	v_mfma_f32_32x32x16_bf16 v[16:31], v[166:169], v[88:91], v[16:31]
	ds_read_b128 v[166:169], v254 offset:4704
	v_mfma_f32_32x32x16_bf16 v[32:47], v[194:197], v[88:91], v[32:47]
	v_mfma_f32_32x32x16_bf16 v[16:31], v[198:201], v[92:95], v[16:31]
	v_mfma_f32_32x32x16_bf16 v[32:47], v[202:205], v[92:95], v[32:47]
	s_waitcnt lgkmcnt(4)
	v_mfma_f32_32x32x16_bf16 v[48:63], v[2:5], v[112:115], v[48:63]
	s_waitcnt lgkmcnt(3)
	v_mfma_f32_32x32x16_bf16 v[64:79], v[6:9], v[108:111], v[64:79]
	s_waitcnt lgkmcnt(2)
	v_mfma_f32_32x32x16_bf16 v[48:63], v[158:161], v[108:111], v[48:63]
	s_waitcnt lgkmcnt(1)
	v_mfma_f32_32x32x16_bf16 v[64:79], v[162:165], v[116:119], v[64:79]
	s_waitcnt lgkmcnt(0)
	v_mfma_f32_32x32x16_bf16 v[48:63], v[166:169], v[116:119], v[48:63]
	s_waitcnt lgkmcnt(0)
	s_barrier
; #define ATT_BAR() do { asm volatile("s_waitcnt lgkmcnt(0)" ::: "memory"); __builtin_amdgcn_s_barrier(); asm volatile("" ::: "memory"); } while (0)
; #define ATT_LD(j, KR, VR) do { KR = *(const u32x4*)(Kb + (kg0 + (long)(j) * 64 * D)); VR = *(const u32x4*)(Vt + (vg0 + (long)(j) * 64)); } while (0)
; #define ATT_ST(j, KR, VR) do { LAS unsigned char* kd_ = lds + ATT_KS + ((j) & 3) * KS_TILE + lr * KS_PITCH + pc * 16; LAS unsigned char* vd_ = lds + ATT_VS + ((j) & 3) * VS_TILE + lr * VS_PITCH + (pc >> 1) * 32 + (pc & 1) * 8;     \
;         *(LAS u32x4*)kd_ = KR; *(LAS u32x2*)vd_ = (u32x2){VR.x, VR.y}; *(LAS u32x2*)(vd_ + 16) = (u32x2){VR.z, VR.w}; } while (0)
; __device__ __forceinline__ void attn_phase(LAS unsigned char* lds, const bf16_t* Q, const bf16_t* Kb, const bf16_t* Vt, bf16_t* O, const float* relb, const float* qn, const float* kn, int vcu, int G) {
;     ...
;         for (int g = jlo; g <= 12; ++g) {
;             const int bcg = g - cw, bcp = bcg - 1;
;             const bool actg = (g <= 11) && bcg >= 0 && bcg <= 8, actp = (g - 1 >= jlo) && bcp >= 0 && bcp <= 8;
;             if (actg) ATT_QK(g, bcg, sc0, sc1);
;             if (actp) ATT_PV(g - 1, pw);
;             ATT_BAR();
;             if (g + 2 <= 11) ATT_ST(g + 2, kreg, vreg);
;             if (g + 3 <= 11) ATT_LD(g + 3, kreg, vreg);
;             if (actg) ATT_SM(sc0, sc1, pw);
;             ATT_BAR();
;         }
	s_waitcnt vmcnt(0)
	ds_write_b128 v255, v[226:229] offset:9216
	v_add_u32_e32 v1, 0x1bc00, v152
	ds_write2_b64 v1, v[222:223], v[224:225] offset1:2
	ds_read_b128 v[2:5], v13
	ds_read_b128 v[6:9], v13 offset:4608
	ds_read_b128 v[158:161], v13 offset:32
	ds_read_b128 v[162:165], v13 offset:4640
	ds_read_b128 v[166:169], v13 offset:64
	ds_read_b128 v[194:197], v13 offset:4672
	ds_read_b128 v[198:201], v13 offset:96
	ds_read_b128 v[202:205], v13 offset:4704
	ds_read_b128 v[234:237], v128
	ds_read_b128 v[238:241], v128 offset:4608
	ds_read_b128 v[242:245], v128 offset:32
	v_exp_f32_e32 v32, v32
	v_exp_f32_e32 v33, v33
	v_exp_f32_e32 v34, v34
	v_exp_f32_e32 v35, v35
	v_exp_f32_e32 v36, v36
	v_add_f32_e32 v10, 0, v32
	v_exp_f32_e32 v37, v37
	v_add_f32_e32 v10, v10, v33
	v_exp_f32_e32 v38, v38
	v_add_f32_e32 v10, v10, v34
	v_exp_f32_e32 v39, v39
	v_add_f32_e32 v10, v10, v35
	v_exp_f32_e32 v40, v40
	v_add_f32_e32 v10, v10, v36
	v_exp_f32_e32 v41, v41
	v_add_f32_e32 v10, v10, v37
	v_exp_f32_e32 v42, v42
	v_add_f32_e32 v10, v10, v38
	v_exp_f32_e32 v43, v43
	v_add_f32_e32 v10, v10, v39
	v_exp_f32_e32 v44, v44
	v_add_f32_e32 v10, v10, v40
	v_exp_f32_e32 v45, v45
	v_add_f32_e32 v10, v10, v41
	v_exp_f32_e32 v46, v46
	v_add_f32_e32 v10, v10, v42
	v_exp_f32_e32 v47, v47
	v_add_f32_e32 v10, v10, v43
	v_add_f32_e32 v10, v10, v44
	v_add_f32_e32 v10, v10, v45
	v_add_f32_e32 v10, v10, v46
	v_add_f32_e32 v10, v10, v47
	v_cvt_pk_bf16_f32 v108, v32, v33
	v_cvt_pk_bf16_f32 v109, v34, v35
	v_cvt_pk_bf16_f32 v110, v36, v37
	v_cvt_pk_bf16_f32 v111, v38, v39
	v_cvt_pk_bf16_f32 v116, v40, v41
	v_cvt_pk_bf16_f32 v117, v42, v43
	v_cvt_pk_bf16_f32 v118, v44, v45
	v_cvt_pk_bf16_f32 v119, v46, v47
	s_waitcnt lgkmcnt(11)
	ds_read_b128 v[32:35], v133 offset:1920
	ds_read_b128 v[36:39], v133 offset:1952
	ds_read_b128 v[40:43], v133 offset:1984
	ds_read_b128 v[44:47], v133 offset:2016
	v_exp_f32_e32 v16, v16
	v_exp_f32_e32 v17, v17
	v_exp_f32_e32 v18, v18
	v_exp_f32_e32 v19, v19
	v_exp_f32_e32 v20, v20
	v_add_f32_e32 v11, 0, v16
	v_exp_f32_e32 v21, v21
	v_add_f32_e32 v11, v11, v17
	v_exp_f32_e32 v22, v22
	v_add_f32_e32 v11, v11, v18
	v_exp_f32_e32 v23, v23
	v_add_f32_e32 v11, v11, v19
	v_exp_f32_e32 v24, v24
	v_add_f32_e32 v11, v11, v20
	v_exp_f32_e32 v25, v25
	v_add_f32_e32 v11, v11, v21
	v_exp_f32_e32 v26, v26
	v_add_f32_e32 v11, v11, v22
	v_exp_f32_e32 v27, v27
	v_add_f32_e32 v11, v11, v23
	v_exp_f32_e32 v28, v28
	v_add_f32_e32 v11, v11, v24
	v_exp_f32_e32 v29, v29
	v_add_f32_e32 v11, v11, v25
	v_exp_f32_e32 v30, v30
	v_add_f32_e32 v11, v11, v26
	v_exp_f32_e32 v31, v31
	v_add_f32_e32 v11, v11, v27
	v_add_f32_e32 v11, v11, v28
	v_add_f32_e32 v11, v11, v29
	v_add_f32_e32 v11, v11, v30
	v_add_f32_e32 v11, v11, v31
	v_cvt_pk_bf16_f32 v104, v16, v17
	v_cvt_pk_bf16_f32 v105, v18, v19
	v_cvt_pk_bf16_f32 v106, v20, v21
	v_cvt_pk_bf16_f32 v107, v22, v23
	v_cvt_pk_bf16_f32 v112, v24, v25
	v_cvt_pk_bf16_f32 v113, v26, v27
	v_cvt_pk_bf16_f32 v114, v28, v29
	v_cvt_pk_bf16_f32 v115, v30, v31
	s_waitcnt lgkmcnt(8)
	ds_read_b128 v[16:19], v133 offset:1792
	ds_read_b128 v[20:23], v133 offset:1824
	ds_read_b128 v[24:27], v133 offset:1856
	ds_read_b128 v[28:31], v133 offset:1888
	v_add_f32_e32 v1, v10, v11
	v_add_f32_e32 v131, v131, v1
	s_barrier
	s_waitcnt lgkmcnt(8)
	v_mfma_f32_32x32x16_bf16 v[64:79], v[234:237], v[104:107], v[64:79]
	v_mfma_f32_32x32x16_bf16 v[48:63], v[238:241], v[104:107], v[48:63]
	v_mfma_f32_32x32x16_bf16 v[64:79], v[242:245], v[112:115], v[64:79]
	s_waitcnt lgkmcnt(0)
	v_mfma_f32_32x32x16_bf16 v[16:31], v[2:5], v[80:83], v[16:31]
	ds_read_b128 v[2:5], v128 offset:4640
	v_mfma_f32_32x32x16_bf16 v[32:47], v[6:9], v[80:83], v[32:47]
	ds_read_b128 v[6:9], v128 offset:64
	v_mfma_f32_32x32x16_bf16 v[16:31], v[158:161], v[84:87], v[16:31]
	ds_read_b128 v[158:161], v128 offset:4672
	v_mfma_f32_32x32x16_bf16 v[32:47], v[162:165], v[84:87], v[32:47]
	ds_read_b128 v[162:165], v128 offset:96
	v_mfma_f32_32x32x16_bf16 v[16:31], v[166:169], v[88:91], v[16:31]
	ds_read_b128 v[166:169], v128 offset:4704
	v_mfma_f32_32x32x16_bf16 v[32:47], v[194:197], v[88:91], v[32:47]
	v_mfma_f32_32x32x16_bf16 v[16:31], v[198:201], v[92:95], v[16:31]
	v_mfma_f32_32x32x16_bf16 v[32:47], v[202:205], v[92:95], v[32:47]
	s_waitcnt lgkmcnt(4)
	v_mfma_f32_32x32x16_bf16 v[48:63], v[2:5], v[112:115], v[48:63]
	s_waitcnt lgkmcnt(3)
	v_mfma_f32_32x32x16_bf16 v[64:79], v[6:9], v[108:111], v[64:79]
	s_waitcnt lgkmcnt(2)
	v_mfma_f32_32x32x16_bf16 v[48:63], v[158:161], v[108:111], v[48:63]
	s_waitcnt lgkmcnt(1)
	v_mfma_f32_32x32x16_bf16 v[64:79], v[162:165], v[116:119], v[64:79]
	s_waitcnt lgkmcnt(0)
	v_mfma_f32_32x32x16_bf16 v[48:63], v[166:169], v[116:119], v[48:63]
	s_waitcnt lgkmcnt(0)
	s_barrier
; #define ATT_BAR() do { asm volatile("s_waitcnt lgkmcnt(0)" ::: "memory"); __builtin_amdgcn_s_barrier(); asm volatile("" ::: "memory"); } while (0)
; #define ATT_LD(j, KR, VR) do { KR = *(const u32x4*)(Kb + (kg0 + (long)(j) * 64 * D)); VR = *(const u32x4*)(Vt + (vg0 + (long)(j) * 64)); } while (0)
; #define ATT_ST(j, KR, VR) do { LAS unsigned char* kd_ = lds + ATT_KS + ((j) & 3) * KS_TILE + lr * KS_PITCH + pc * 16; LAS unsigned char* vd_ = lds + ATT_VS + ((j) & 3) * VS_TILE + lr * VS_PITCH + (pc >> 1) * 32 + (pc & 1) * 8;     \
;         *(LAS u32x4*)kd_ = KR; *(LAS u32x2*)vd_ = (u32x2){VR.x, VR.y}; *(LAS u32x2*)(vd_ + 16) = (u32x2){VR.z, VR.w}; } while (0)
; __device__ __forceinline__ void attn_phase(LAS unsigned char* lds, const bf16_t* Q, const bf16_t* Kb, const bf16_t* Vt, bf16_t* O, const float* relb, const float* qn, const float* kn, int vcu, int G) {
;     ...
;         for (int g = jlo; g <= 12; ++g) {
;             const int bcg = g - cw, bcp = bcg - 1;
;             const bool actg = (g <= 11) && bcg >= 0 && bcg <= 8, actp = (g - 1 >= jlo) && bcp >= 0 && bcp <= 8;
;             if (actg) ATT_QK(g, bcg, sc0, sc1);
;             if (actp) ATT_PV(g - 1, pw);
;             ATT_BAR();
;             if (g + 2 <= 11) ATT_ST(g + 2, kreg, vreg);
;             if (g + 3 <= 11) ATT_LD(g + 3, kreg, vreg);
;             if (actg) ATT_SM(sc0, sc1, pw);
;             ATT_BAR();
;         }
	s_waitcnt vmcnt(0)
	v_add_u32_e32 v1, 0x1e000, v152
	ds_write2_b64 v1, v[230:231], v[232:233] offset1:2
	ds_read_b128 v[2:5], v14
	ds_read_b128 v[6:9], v14 offset:4608
	ds_read_b128 v[158:161], v14 offset:32
	ds_read_b128 v[162:165], v14 offset:4640
	ds_read_b128 v[166:169], v14 offset:64
	ds_read_b128 v[194:197], v14 offset:4672
	ds_read_b128 v[198:201], v14 offset:96
	ds_read_b128 v[202:205], v14 offset:4704
	ds_read_b128 v[234:237], v129
	ds_read_b128 v[238:241], v129 offset:4608
	ds_read_b128 v[242:245], v129 offset:32
	v_exp_f32_e32 v32, v32
	v_exp_f32_e32 v33, v33
	v_exp_f32_e32 v34, v34
	v_exp_f32_e32 v35, v35
	v_exp_f32_e32 v36, v36
	v_add_f32_e32 v10, 0, v32
	v_exp_f32_e32 v37, v37
	v_add_f32_e32 v10, v10, v33
	v_exp_f32_e32 v38, v38
	v_add_f32_e32 v10, v10, v34
	v_exp_f32_e32 v39, v39
	v_add_f32_e32 v10, v10, v35
	v_exp_f32_e32 v40, v40
	v_add_f32_e32 v10, v10, v36
	v_exp_f32_e32 v41, v41
	v_add_f32_e32 v10, v10, v37
	v_exp_f32_e32 v42, v42
	v_add_f32_e32 v10, v10, v38
	v_exp_f32_e32 v43, v43
	v_add_f32_e32 v10, v10, v39
	v_exp_f32_e32 v44, v44
	v_add_f32_e32 v10, v10, v40
	v_exp_f32_e32 v45, v45
	v_add_f32_e32 v10, v10, v41
	v_exp_f32_e32 v46, v46
	v_add_f32_e32 v10, v10, v42
	v_exp_f32_e32 v47, v47
	v_add_f32_e32 v10, v10, v43
	v_add_f32_e32 v10, v10, v44
	v_add_f32_e32 v10, v10, v45
	v_add_f32_e32 v10, v10, v46
	v_add_f32_e32 v10, v10, v47
	v_cvt_pk_bf16_f32 v108, v32, v33
	v_cvt_pk_bf16_f32 v109, v34, v35
	v_cvt_pk_bf16_f32 v110, v36, v37
	v_cvt_pk_bf16_f32 v111, v38, v39
	v_cvt_pk_bf16_f32 v116, v40, v41
	v_cvt_pk_bf16_f32 v117, v42, v43
	v_cvt_pk_bf16_f32 v118, v44, v45
	v_cvt_pk_bf16_f32 v119, v46, v47
	s_waitcnt lgkmcnt(11)
	ds_read_b128 v[32:35], v133 offset:2176
	ds_read_b128 v[36:39], v133 offset:2208
	ds_read_b128 v[40:43], v133 offset:2240
	ds_read_b128 v[44:47], v133 offset:2272
	v_exp_f32_e32 v16, v16
	v_exp_f32_e32 v17, v17
	v_exp_f32_e32 v18, v18
	v_exp_f32_e32 v19, v19
	v_exp_f32_e32 v20, v20
	v_add_f32_e32 v11, 0, v16
	v_exp_f32_e32 v21, v21
	v_add_f32_e32 v11, v11, v17
	v_exp_f32_e32 v22, v22
	v_add_f32_e32 v11, v11, v18
	v_exp_f32_e32 v23, v23
	v_add_f32_e32 v11, v11, v19
	v_exp_f32_e32 v24, v24
	v_add_f32_e32 v11, v11, v20
	v_exp_f32_e32 v25, v25
	v_add_f32_e32 v11, v11, v21
	v_exp_f32_e32 v26, v26
	v_add_f32_e32 v11, v11, v22
	v_exp_f32_e32 v27, v27
	v_add_f32_e32 v11, v11, v23
	v_exp_f32_e32 v28, v28
	v_add_f32_e32 v11, v11, v24
	v_exp_f32_e32 v29, v29
	v_add_f32_e32 v11, v11, v25
	v_exp_f32_e32 v30, v30
	v_add_f32_e32 v11, v11, v26
	v_exp_f32_e32 v31, v31
	v_add_f32_e32 v11, v11, v27
	v_add_f32_e32 v11, v11, v28
	v_add_f32_e32 v11, v11, v29
	v_add_f32_e32 v11, v11, v30
	v_add_f32_e32 v11, v11, v31
	v_cvt_pk_bf16_f32 v104, v16, v17
	v_cvt_pk_bf16_f32 v105, v18, v19
	v_cvt_pk_bf16_f32 v106, v20, v21
	v_cvt_pk_bf16_f32 v107, v22, v23
	v_cvt_pk_bf16_f32 v112, v24, v25
	v_cvt_pk_bf16_f32 v113, v26, v27
	v_cvt_pk_bf16_f32 v114, v28, v29
	v_cvt_pk_bf16_f32 v115, v30, v31
	s_waitcnt lgkmcnt(8)
	ds_read_b128 v[16:19], v133 offset:2048
	ds_read_b128 v[20:23], v133 offset:2080
	ds_read_b128 v[24:27], v133 offset:2112
	ds_read_b128 v[28:31], v133 offset:2144
	v_add_f32_e32 v1, v10, v11
	v_add_f32_e32 v131, v131, v1
	s_barrier
	s_waitcnt lgkmcnt(8)
	v_mfma_f32_32x32x16_bf16 v[64:79], v[234:237], v[104:107], v[64:79]
	v_mfma_f32_32x32x16_bf16 v[48:63], v[238:241], v[104:107], v[48:63]
	v_mfma_f32_32x32x16_bf16 v[64:79], v[242:245], v[112:115], v[64:79]
	s_waitcnt lgkmcnt(0)
	v_mfma_f32_32x32x16_bf16 v[16:31], v[2:5], v[80:83], v[16:31]
	ds_read_b128 v[2:5], v129 offset:4640
	v_mfma_f32_32x32x16_bf16 v[32:47], v[6:9], v[80:83], v[32:47]
	ds_read_b128 v[6:9], v129 offset:64
	v_mfma_f32_32x32x16_bf16 v[16:31], v[158:161], v[84:87], v[16:31]
	ds_read_b128 v[158:161], v129 offset:4672
	v_mfma_f32_32x32x16_bf16 v[32:47], v[162:165], v[84:87], v[32:47]
	ds_read_b128 v[162:165], v129 offset:96
	v_mfma_f32_32x32x16_bf16 v[16:31], v[166:169], v[88:91], v[16:31]
	ds_read_b128 v[166:169], v129 offset:4704
	v_mfma_f32_32x32x16_bf16 v[32:47], v[194:197], v[88:91], v[32:47]
	v_mfma_f32_32x32x16_bf16 v[16:31], v[198:201], v[92:95], v[16:31]
	v_mfma_f32_32x32x16_bf16 v[32:47], v[202:205], v[92:95], v[32:47]
	s_waitcnt lgkmcnt(4)
	v_mfma_f32_32x32x16_bf16 v[48:63], v[2:5], v[112:115], v[48:63]
	s_waitcnt lgkmcnt(3)
	v_mfma_f32_32x32x16_bf16 v[64:79], v[6:9], v[108:111], v[64:79]
	s_waitcnt lgkmcnt(2)
	v_mfma_f32_32x32x16_bf16 v[48:63], v[158:161], v[108:111], v[48:63]
	s_waitcnt lgkmcnt(1)
	v_mfma_f32_32x32x16_bf16 v[64:79], v[162:165], v[116:119], v[64:79]
	s_waitcnt lgkmcnt(0)
	v_mfma_f32_32x32x16_bf16 v[48:63], v[166:169], v[116:119], v[48:63]
	s_waitcnt lgkmcnt(0)
	s_barrier
; #define ATT_BAR() do { asm volatile("s_waitcnt lgkmcnt(0)" ::: "memory"); __builtin_amdgcn_s_barrier(); asm volatile("" ::: "memory"); } while (0)
; #define ATT_LD(j, KR, VR) do { KR = *(const u32x4*)(Kb + (kg0 + (long)(j) * 64 * D)); VR = *(const u32x4*)(Vt + (vg0 + (long)(j) * 64)); } while (0)
; #define ATT_ST(j, KR, VR) do { LAS unsigned char* kd_ = lds + ATT_KS + ((j) & 3) * KS_TILE + lr * KS_PITCH + pc * 16; LAS unsigned char* vd_ = lds + ATT_VS + ((j) & 3) * VS_TILE + lr * VS_PITCH + (pc >> 1) * 32 + (pc & 1) * 8;     \
;         *(LAS u32x4*)kd_ = KR; *(LAS u32x2*)vd_ = (u32x2){VR.x, VR.y}; *(LAS u32x2*)(vd_ + 16) = (u32x2){VR.z, VR.w}; } while (0)
; __device__ __forceinline__ void attn_phase(LAS unsigned char* lds, const bf16_t* Q, const bf16_t* Kb, const bf16_t* Vt, bf16_t* O, const float* relb, const float* qn, const float* kn, int vcu, int G) {
;     ...
;         const int jlo = (qb < 2) ? 8 - 4 * qb : 0;
;         const long kg0 = ((long)rowbase + (long)(4 * qb - 8) * 64 + lr) * D + h * 64 + pc * 8;
;         const long vg0 = (long)(h * 64 + lr) * M + (long)rowbase + (long)(4 * qb - 8) * 64 + pc * 8;
;         u32x4 kreg, vreg;
;         { u32x4 ka, va, kb2, vb2; ATT_LD(jlo, ka, va); ATT_LD(jlo + 1, kb2, vb2); ATT_LD(jlo + 2, kreg, vreg);
;           ATT_ST(jlo, ka, va); ATT_ST(jlo + 1, kb2, vb2); }
;         bf16x8 qr[4];
;         { const bf16_t* qp = Q + (rowbase + (size_t)qb * 256 + w * 32 + r32) * D + h * 64 + hi * 8;
; #pragma unroll
;           for (int d0 = 0; d0 < 4; ++d0) qr[d0] = *(const bf16x8*)(qp + d0 * 16); }
;         __syncthreads();
;         float lrun = 0.f; f32x16 o0 = {}, o1 = {}, sc0 = {}, sc1 = {}; bf16x8 pw[4] = {};
;         if (half == 1) ATT_BAR();
;         for (int g = jlo; g <= 12; ++g) {
;             const int bcg = g - cw, bcp = bcg - 1;
;             const bool actg = (g <= 11) && bcg >= 0 && bcg <= 8, actp = (g - 1 >= jlo) && bcp >= 0 && bcp <= 8;
;             if (actg) ATT_QK(g, bcg, sc0, sc1);
;             if (actp) ATT_PV(g - 1, pw);
;             ATT_BAR();
;             if (g + 2 <= 11) ATT_ST(g + 2, kreg, vreg);
;             if (g + 3 <= 11) ATT_LD(g + 3, kreg, vreg);
;             if (actg) ATT_SM(sc0, sc1, pw);
;             ATT_BAR();
;         }
	ds_read_b128 v[234:237], v157
	ds_read_b128 v[238:241], v157 offset:4608
	ds_read_b128 v[242:245], v157 offset:32
	v_exp_f32_e32 v32, v32
	v_exp_f32_e32 v33, v33
	v_exp_f32_e32 v34, v34
	v_exp_f32_e32 v35, v35
	v_exp_f32_e32 v36, v36
	v_add_f32_e32 v10, 0, v32
	v_exp_f32_e32 v37, v37
	v_add_f32_e32 v10, v10, v33
	v_exp_f32_e32 v38, v38
	v_add_f32_e32 v10, v10, v34
	v_exp_f32_e32 v39, v39
	v_add_f32_e32 v10, v10, v35
	v_exp_f32_e32 v40, v40
	v_add_f32_e32 v10, v10, v36
	v_exp_f32_e32 v41, v41
	v_add_f32_e32 v10, v10, v37
	v_exp_f32_e32 v42, v42
	v_add_f32_e32 v10, v10, v38
	v_exp_f32_e32 v43, v43
	v_add_f32_e32 v10, v10, v39
	v_exp_f32_e32 v44, v44
	v_add_f32_e32 v10, v10, v40
	v_exp_f32_e32 v45, v45
	v_add_f32_e32 v10, v10, v41
	v_exp_f32_e32 v46, v46
	v_add_f32_e32 v10, v10, v42
	v_exp_f32_e32 v47, v47
	v_add_f32_e32 v10, v10, v43
	v_add_f32_e32 v10, v10, v44
	v_add_f32_e32 v10, v10, v45
	v_add_f32_e32 v10, v10, v46
	v_add_f32_e32 v10, v10, v47
	v_cvt_pk_bf16_f32 v108, v32, v33
	v_cvt_pk_bf16_f32 v109, v34, v35
	v_cvt_pk_bf16_f32 v110, v36, v37
	v_cvt_pk_bf16_f32 v111, v38, v39
	v_cvt_pk_bf16_f32 v116, v40, v41
	v_cvt_pk_bf16_f32 v117, v42, v43
	v_cvt_pk_bf16_f32 v118, v44, v45
	v_cvt_pk_bf16_f32 v119, v46, v47
	v_exp_f32_e32 v16, v16
	v_exp_f32_e32 v17, v17
	v_exp_f32_e32 v18, v18
	v_exp_f32_e32 v19, v19
	v_exp_f32_e32 v20, v20
	v_add_f32_e32 v11, 0, v16
	v_exp_f32_e32 v21, v21
	v_add_f32_e32 v11, v11, v17
	v_exp_f32_e32 v22, v22
	v_add_f32_e32 v11, v11, v18
	v_exp_f32_e32 v23, v23
	v_add_f32_e32 v11, v11, v19
	v_exp_f32_e32 v24, v24
	v_add_f32_e32 v11, v11, v20
	v_exp_f32_e32 v25, v25
	v_add_f32_e32 v11, v11, v21
	v_exp_f32_e32 v26, v26
	v_add_f32_e32 v11, v11, v22
	v_exp_f32_e32 v27, v27
	v_add_f32_e32 v11, v11, v23
	v_exp_f32_e32 v28, v28
	v_add_f32_e32 v11, v11, v24
	v_exp_f32_e32 v29, v29
	v_add_f32_e32 v11, v11, v25
	v_exp_f32_e32 v30, v30
	v_add_f32_e32 v11, v11, v26
	v_exp_f32_e32 v31, v31
	v_add_f32_e32 v11, v11, v27
	v_add_f32_e32 v11, v11, v28
	v_add_f32_e32 v11, v11, v29
	v_add_f32_e32 v11, v11, v30
	v_add_f32_e32 v11, v11, v31
	v_cvt_pk_bf16_f32 v104, v16, v17
	v_cvt_pk_bf16_f32 v105, v18, v19
	v_cvt_pk_bf16_f32 v106, v20, v21
	v_cvt_pk_bf16_f32 v107, v22, v23
	v_cvt_pk_bf16_f32 v112, v24, v25
	v_cvt_pk_bf16_f32 v113, v26, v27
	v_cvt_pk_bf16_f32 v114, v28, v29
	v_cvt_pk_bf16_f32 v115, v30, v31
	v_add_f32_e32 v1, v10, v11
	v_add_f32_e32 v131, v131, v1
	s_barrier
	ds_read_b128 v[2:5], v157 offset:4640
	ds_read_b128 v[6:9], v157 offset:64
	ds_read_b128 v[158:161], v157 offset:4672
	ds_read_b128 v[162:165], v157 offset:96
	ds_read_b128 v[166:169], v157 offset:4704
	s_waitcnt lgkmcnt(5)
	v_mfma_f32_32x32x16_bf16 v[64:79], v[234:237], v[104:107], v[64:79]
	v_mfma_f32_32x32x16_bf16 v[48:63], v[238:241], v[104:107], v[48:63]
	v_mfma_f32_32x32x16_bf16 v[64:79], v[242:245], v[112:115], v[64:79]
	s_waitcnt lgkmcnt(4)
	v_mfma_f32_32x32x16_bf16 v[48:63], v[2:5], v[112:115], v[48:63]
	s_waitcnt lgkmcnt(3)
	v_mfma_f32_32x32x16_bf16 v[64:79], v[6:9], v[108:111], v[64:79]
	s_waitcnt lgkmcnt(2)
	v_mfma_f32_32x32x16_bf16 v[48:63], v[158:161], v[108:111], v[48:63]
	s_waitcnt lgkmcnt(1)
	v_mfma_f32_32x32x16_bf16 v[64:79], v[162:165], v[116:119], v[64:79]
	s_waitcnt lgkmcnt(0)
	v_mfma_f32_32x32x16_bf16 v[48:63], v[166:169], v[116:119], v[48:63]
	s_waitcnt lgkmcnt(0)
	s_barrier
	s_branch .Lag_exit
.Lap_jnz:
	s_mov_b64 s[76:77], 0x80000
	v_lshl_add_u64 v[140:141], v[140:141], 0, s[76:77]
	s_cmp_gt_u32 s40, 4
	s_cbranch_scc1 .Lap_j8
	global_load_dwordx4 v[34:37], v[140:141], off
	v_lshl_add_u64 v[140:141], v[140:141], 0, s[44:45]
	global_load_dwordx4 v[80:83], v[38:39], off
	global_load_dwordx4 v[84:87], v[38:39], off offset:32
	global_load_dwordx4 v[88:91], v[38:39], off offset:64
	global_load_dwordx4 v[92:95], v[38:39], off offset:96
	global_load_dwordx4 v[226:229], v[140:141], off
	global_load_dwordx4 v[222:225], v[138:139], off offset:512
	v_lshl_add_u64 v[140:141], v[140:141], 0, s[44:45]
	global_load_dwordx4 v[96:99], v[140:141], off
	global_load_dwordx4 v[230:233], v[138:139], off offset:640
	v_lshl_add_u64 v[140:141], v[140:141], 0, s[44:45]
	global_load_dwordx4 v[218:221], v[140:141], off
	global_load_dwordx4 v[100:103], v[138:139], off offset:768
	v_lshl_add_u64 v[140:141], v[140:141], 0, s[44:45]
	s_movk_i32 s80, 0x380
	v_lshl_add_u64 v[138:139], v[138:139], 0, s[80:81]
	s_waitcnt vmcnt(10)
	v_add_u32_e32 v14, 0x17400, v151
	ds_write_b128 v14, v[34:37]
	s_waitcnt vmcnt(6)
	s_branch .Lap_common
; #define ATT_BAR() do { asm volatile("s_waitcnt lgkmcnt(0)" ::: "memory"); __builtin_amdgcn_s_barrier(); asm volatile("" ::: "memory"); } while (0)
; #define ATT_LD(j, KR, VR) do { KR = *(const u32x4*)(Kb + (kg0 + (long)(j) * 64 * D)); VR = *(const u32x4*)(Vt + (vg0 + (long)(j) * 64)); } while (0)
; #define ATT_ST(j, KR, VR) do { LAS unsigned char* kd_ = lds + ATT_KS + ((j) & 3) * KS_TILE + lr * KS_PITCH + pc * 16; LAS unsigned char* vd_ = lds + ATT_VS + ((j) & 3) * VS_TILE + lr * VS_PITCH + (pc >> 1) * 32 + (pc & 1) * 8;     \
;         *(LAS u32x4*)kd_ = KR; *(LAS u32x2*)vd_ = (u32x2){VR.x, VR.y}; *(LAS u32x2*)(vd_ + 16) = (u32x2){VR.z, VR.w}; } while (0)
; __device__ __forceinline__ void attn_phase(LAS unsigned char* lds, const bf16_t* Q, const bf16_t* Kb, const bf16_t* Vt, bf16_t* O, const float* relb, const float* qn, const float* kn, int vcu, int G) {
;     ...
;         const int jlo = (qb < 2) ? 8 - 4 * qb : 0;
;         const long kg0 = ((long)rowbase + (long)(4 * qb - 8) * 64 + lr) * D + h * 64 + pc * 8;
;         const long vg0 = (long)(h * 64 + lr) * M + (long)rowbase + (long)(4 * qb - 8) * 64 + pc * 8;
;         u32x4 kreg, vreg;
;         { u32x4 ka, va, kb2, vb2; ATT_LD(jlo, ka, va); ATT_LD(jlo + 1, kb2, vb2); ATT_LD(jlo + 2, kreg, vreg);
;           ATT_ST(jlo, ka, va); ATT_ST(jlo + 1, kb2, vb2); }
;         bf16x8 qr[4];
;         { const bf16_t* qp = Q + (rowbase + (size_t)qb * 256 + w * 32 + r32) * D + h * 64 + hi * 8;
; #pragma unroll
;           for (int d0 = 0; d0 < 4; ++d0) qr[d0] = *(const bf16x8*)(qp + d0 * 16); }
;         __syncthreads();
;         float lrun = 0.f; f32x16 o0 = {}, o1 = {}, sc0 = {}, sc1 = {}; bf16x8 pw[4] = {};
;         if (half == 1) ATT_BAR();
;         for (int g = jlo; g <= 12; ++g) {
;             const int bcg = g - cw, bcp = bcg - 1;
;             const bool actg = (g <= 11) && bcg >= 0 && bcg <= 8, actp = (g - 1 >= jlo) && bcp >= 0 && bcp <= 8;
;             if (actg) ATT_QK(g, bcg, sc0, sc1);
;             if (actp) ATT_PV(g - 1, pw);
;             ATT_BAR();
;             if (g + 2 <= 11) ATT_ST(g + 2, kreg, vreg);
;             if (g + 3 <= 11) ATT_LD(g + 3, kreg, vreg);
;             if (actg) ATT_SM(sc0, sc1, pw);
;             ATT_BAR();
.Lap_j8:
	global_load_dwordx4 v[80:83], v[38:39], off
	global_load_dwordx4 v[84:87], v[38:39], off offset:32
	global_load_dwordx4 v[88:91], v[38:39], off offset:64
	global_load_dwordx4 v[92:95], v[38:39], off offset:96
	s_mov_b64 s[76:77], 0x80000
	v_lshl_add_u64 v[140:141], v[140:141], 0, s[76:77]
	s_movk_i32 s80, 0x380
	v_lshl_add_u64 v[138:139], v[138:139], 0, s[80:81]
	s_waitcnt vmcnt(0)
.Lap_common:
	s_lshr_b32 s49, s43, 3
	s_mulk_i32 s49, 0x2900
	s_add_i32 s49, s49, 0x12000
	v_add_u32_e32 v133, s49, v148
	v_add_u32_e32 v133, v133, v149
	v_mov_b32_e32 v48, v0
	v_mov_b32_e32 v49, v0
	v_mov_b64_e32 v[50:51], v[48:49]
	v_mov_b64_e32 v[52:53], v[48:49]
	v_mov_b64_e32 v[54:55], v[48:49]
	v_mov_b64_e32 v[56:57], v[48:49]
	v_mov_b64_e32 v[58:59], v[48:49]
	v_mov_b64_e32 v[60:61], v[48:49]
	v_mov_b64_e32 v[62:63], v[48:49]
	v_mov_b64_e32 v[64:65], v[48:49]
	v_mov_b64_e32 v[66:67], v[48:49]
	v_mov_b64_e32 v[68:69], v[48:49]
	v_mov_b64_e32 v[70:71], v[48:49]
	v_mov_b64_e32 v[72:73], v[48:49]
	v_mov_b64_e32 v[74:75], v[48:49]
	v_mov_b64_e32 v[76:77], v[48:49]
	v_mov_b64_e32 v[78:79], v[48:49]
	v_mov_b32_e32 v1, s49
	s_waitcnt lgkmcnt(0)
	s_barrier
	ds_read_b32 v246, v1
	s_mov_b32 s18, 0
	s_mov_b32 s19, 0
	s_waitcnt lgkmcnt(0)
	v_mov_b32_e32 v247, v246
	s_sub_i32 s20, s19, s28
	s_cmp_lt_u32 s19, 9
	s_cselect_b64 s[42:43], -1, 0
	s_cmp_ge_u32 s20, s40
	s_cselect_b64 s[48:49], -1, 0
	s_and_b64 s[42:43], s[42:43], s[48:49]
	s_not_b64 s[76:77], s[42:43]
	s_add_i32 s21, s19, -1
	s_cmp_lt_u32 s21, 9
	s_cselect_b64 s[48:49], -1, 0
	s_cmp_gt_u32 s20, s40
	s_cselect_b64 s[80:81], -1, 0
	s_and_b64 s[48:49], s[48:49], s[80:81]
	s_add_i32 s21, s20, -1
	s_add_i32 s80, s21, -6
	s_cmp_gt_u32 s21, 5
	s_cselect_b32 s80, s80, s21
	s_mul_i32 s41, s80, 0x2400
	s_cmp_gt_u32 s80, 3
	s_cselect_b32 s80, 0xe400, 0
	s_cselect_b32 s53, 0x4800, 0
	s_add_i32 s41, s41, s80
	s_sub_i32 s53, s41, s53
	s_add_i32 s53, s53, 0x9000
	v_add_u32_e32 v217, s53, v153
	s_add_i32 s80, s20, -6
	s_cmp_gt_u32 s20, 5
	s_cselect_b32 s80, s80, s20
	s_mul_i32 s41, s80, 0x2400
	s_cmp_gt_u32 s80, 3
	s_cselect_b32 s80, 0xe400, 0
	s_cselect_b32 s53, 0x4800, 0
	s_add_i32 s41, s41, s80
	s_sub_i32 s53, s41, s53
	s_add_i32 s53, s53, 0x9000
	v_add_u32_e32 v1, s41, v153
	s_and_b64 s[80:81], exec, s[42:43]
	s_cbranch_scc0 .Lpf_none_p
	s_waitcnt lgkmcnt(0)
	s_cmp_lt_u32 s19, 4
	s_cbranch_scc0 .Lpf_tbl_p
	ds_read_b128 v[2:5], v1
	ds_read_b128 v[6:9], v1 offset:4608
	ds_read_b128 v[158:161], v1 offset:32
	ds_read_b128 v[162:165], v1 offset:4640
	ds_read_b128 v[166:169], v1 offset:64
	ds_read_b128 v[194:197], v1 offset:4672
	ds_read_b128 v[198:201], v1 offset:96
	ds_read_b128 v[202:205], v1 offset:4704
	v_mov_b64_e32 v[16:17], v[246:247]
	v_mov_b64_e32 v[18:19], v[246:247]
	v_mov_b64_e32 v[20:21], v[246:247]
	v_mov_b64_e32 v[22:23], v[246:247]
	v_mov_b64_e32 v[24:25], v[246:247]
	v_mov_b64_e32 v[26:27], v[246:247]
	v_mov_b64_e32 v[28:29], v[246:247]
	v_mov_b64_e32 v[30:31], v[246:247]
	v_mov_b64_e32 v[32:33], v[246:247]
	v_mov_b64_e32 v[34:35], v[246:247]
	v_mov_b64_e32 v[36:37], v[246:247]
	v_mov_b64_e32 v[38:39], v[246:247]
	v_mov_b64_e32 v[40:41], v[246:247]
	v_mov_b64_e32 v[42:43], v[246:247]
	v_mov_b64_e32 v[44:45], v[246:247]
	v_mov_b64_e32 v[46:47], v[246:247]
	s_waitcnt lgkmcnt(8)
	s_branch .Lpf_done_p
.Lpf_tbl_p:
	ds_read_b128 v[2:5], v1
	ds_read_b128 v[16:19], v133
	ds_read_b128 v[20:23], v133 offset:32
	ds_read_b128 v[24:27], v133 offset:64
	ds_read_b128 v[28:31], v133 offset:96
	ds_read_b128 v[6:9], v1 offset:4608
	ds_read_b128 v[32:35], v133 offset:128
	ds_read_b128 v[36:39], v133 offset:160
	ds_read_b128 v[40:43], v133 offset:192
	ds_read_b128 v[44:47], v133 offset:224
	ds_read_b128 v[158:161], v1 offset:32
	ds_read_b128 v[162:165], v1 offset:4640
	ds_read_b128 v[166:169], v1 offset:64
	ds_read_b128 v[194:197], v1 offset:4672
	ds_read_b128 v[198:201], v1 offset:96
	s_waitcnt lgkmcnt(14)
	ds_read_b128 v[202:205], v1 offset:4704
	s_waitcnt lgkmcnt(15)
	s_branch .Lpf_done_p

; #define ATT_BAR() do { asm volatile("s_waitcnt lgkmcnt(0)" ::: "memory"); __builtin_amdgcn_s_barrier(); asm volatile("" ::: "memory"); } while (0)
; #define ATT_LD(j, KR, VR) do { KR = *(const u32x4*)(Kb + (kg0 + (long)(j) * 64 * D)); VR = *(const u32x4*)(Vt + (vg0 + (long)(j) * 64)); } while (0)
; #define ATT_ST(j, KR, VR) do { LAS unsigned char* kd_ = lds + ATT_KS + ((j) & 3) * KS_TILE + lr * KS_PITCH + pc * 16; LAS unsigned char* vd_ = lds + ATT_VS + ((j) & 3) * VS_TILE + lr * VS_PITCH + (pc >> 1) * 32 + (pc & 1) * 8;     \
;         *(LAS u32x4*)kd_ = KR; *(LAS u32x2*)vd_ = (u32x2){VR.x, VR.y}; *(LAS u32x2*)(vd_ + 16) = (u32x2){VR.z, VR.w}; } while (0)
; __device__ __forceinline__ void attn_phase(LAS unsigned char* lds, const bf16_t* Q, const bf16_t* Kb, const bf16_t* Vt, bf16_t* O, const float* relb, const float* qn, const float* kn, int vcu, int G) {
;     ...
;         for (int g = jlo; g <= 12; ++g) {
;             const int bcg = g - cw, bcp = bcg - 1;
;             const bool actg = (g <= 11) && bcg >= 0 && bcg <= 8, actp = (g - 1 >= jlo) && bcp >= 0 && bcp <= 8;
;             if (actg) ATT_QK(g, bcg, sc0, sc1);
;             if (actp) ATT_PV(g - 1, pw);
;             ATT_BAR();
;             if (g + 2 <= 11) ATT_ST(g + 2, kreg, vreg);
;             if (g + 3 <= 11) ATT_LD(g + 3, kreg, vreg);
;             if (actg) ATT_SM(sc0, sc1, pw);
;             ATT_BAR();
;         }
.Lpf_done_p:
	s_andn2_b64 vcc, exec, s[0:1]
	s_cbranch_vccnz .Lag_0
	s_barrier
.Lag_0:
	s_and_b64 s[20:21], s[42:43], s[48:49]
	s_cbranch_scc1 .Lam_both_0
	s_and_b64 s[20:21], exec, s[42:43]
	s_cbranch_scc1 .Lam_qk_0
	s_and_b64 s[20:21], exec, s[48:49]
	s_cbranch_scc1 .Lam_pv_0
	s_branch .Lam_done_0
.Lam_both_0:
	s_waitcnt lgkmcnt(12)
	ds_read_b128 v[234:237], v217
	ds_read_b128 v[238:241], v217 offset:4608
	ds_read_b128 v[242:245], v217 offset:32
	s_waitcnt lgkmcnt(3)
	v_mfma_f32_32x32x16_bf16 v[16:31], v[2:5], v[80:83], v[16:31]
	ds_read_b128 v[2:5], v217 offset:4640
	v_mfma_f32_32x32x16_bf16 v[32:47], v[6:9], v[80:83], v[32:47]
	ds_read_b128 v[6:9], v217 offset:64
	v_mfma_f32_32x32x16_bf16 v[16:31], v[158:161], v[84:87], v[16:31]
	ds_read_b128 v[158:161], v217 offset:4672
	v_mfma_f32_32x32x16_bf16 v[32:47], v[162:165], v[84:87], v[32:47]
	ds_read_b128 v[162:165], v217 offset:96
	v_mfma_f32_32x32x16_bf16 v[16:31], v[166:169], v[88:91], v[16:31]
	ds_read_b128 v[166:169], v217 offset:4704
	v_mfma_f32_32x32x16_bf16 v[32:47], v[194:197], v[88:91], v[32:47]
	v_mfma_f32_32x32x16_bf16 v[16:31], v[198:201], v[92:95], v[16:31]
	v_mfma_f32_32x32x16_bf16 v[32:47], v[202:205], v[92:95], v[32:47]
	s_waitcnt lgkmcnt(7)
	v_mfma_f32_32x32x16_bf16 v[64:79], v[234:237], v[104:107], v[64:79]
	s_waitcnt lgkmcnt(6)
	v_mfma_f32_32x32x16_bf16 v[48:63], v[238:241], v[104:107], v[48:63]
	s_waitcnt lgkmcnt(5)
	v_mfma_f32_32x32x16_bf16 v[64:79], v[242:245], v[112:115], v[64:79]
	s_waitcnt lgkmcnt(4)
	v_mfma_f32_32x32x16_bf16 v[48:63], v[2:5], v[112:115], v[48:63]
	s_waitcnt lgkmcnt(3)
	v_mfma_f32_32x32x16_bf16 v[64:79], v[6:9], v[108:111], v[64:79]
	s_waitcnt lgkmcnt(2)
	v_mfma_f32_32x32x16_bf16 v[48:63], v[158:161], v[108:111], v[48:63]
	s_waitcnt lgkmcnt(1)
	v_mfma_f32_32x32x16_bf16 v[64:79], v[162:165], v[116:119], v[64:79]
	s_waitcnt lgkmcnt(0)
	v_mfma_f32_32x32x16_bf16 v[48:63], v[166:169], v[116:119], v[48:63]
	s_branch .Lam_done_0
.Lam_qk_0:
	s_waitcnt lgkmcnt(0)
	v_mfma_f32_32x32x16_bf16 v[16:31], v[2:5], v[80:83], v[16:31]
	v_mfma_f32_32x32x16_bf16 v[32:47], v[6:9], v[80:83], v[32:47]
	v_mfma_f32_32x32x16_bf16 v[16:31], v[158:161], v[84:87], v[16:31]
	v_mfma_f32_32x32x16_bf16 v[32:47], v[162:165], v[84:87], v[32:47]
	v_mfma_f32_32x32x16_bf16 v[16:31], v[166:169], v[88:91], v[16:31]
	v_mfma_f32_32x32x16_bf16 v[32:47], v[194:197], v[88:91], v[32:47]
	v_mfma_f32_32x32x16_bf16 v[16:31], v[198:201], v[92:95], v[16:31]
	v_mfma_f32_32x32x16_bf16 v[32:47], v[202:205], v[92:95], v[32:47]
	s_nop 7
	s_branch .Lam_done_0
.Lam_pv_0:
	ds_read_b128 v[234:237], v217
	ds_read_b128 v[238:241], v217 offset:4608
	ds_read_b128 v[242:245], v217 offset:32
	ds_read_b128 v[2:5], v217 offset:4640
	ds_read_b128 v[6:9], v217 offset:64
	ds_read_b128 v[158:161], v217 offset:4672
	ds_read_b128 v[162:165], v217 offset:96
	ds_read_b128 v[166:169], v217 offset:4704
	s_waitcnt lgkmcnt(7)
	v_mfma_f32_32x32x16_bf16 v[64:79], v[234:237], v[104:107], v[64:79]
	s_waitcnt lgkmcnt(6)
	v_mfma_f32_32x32x16_bf16 v[48:63], v[238:241], v[104:107], v[48:63]
	s_waitcnt lgkmcnt(5)
	v_mfma_f32_32x32x16_bf16 v[64:79], v[242:245], v[112:115], v[64:79]
	s_waitcnt lgkmcnt(4)
	v_mfma_f32_32x32x16_bf16 v[48:63], v[2:5], v[112:115], v[48:63]
	s_waitcnt lgkmcnt(3)
	v_mfma_f32_32x32x16_bf16 v[64:79], v[6:9], v[108:111], v[64:79]
	s_waitcnt lgkmcnt(2)
	v_mfma_f32_32x32x16_bf16 v[48:63], v[158:161], v[108:111], v[48:63]
	s_waitcnt lgkmcnt(1)
	v_mfma_f32_32x32x16_bf16 v[64:79], v[162:165], v[116:119], v[64:79]
	s_waitcnt lgkmcnt(0)
	v_mfma_f32_32x32x16_bf16 v[48:63], v[166:169], v[116:119], v[48:63]
.Lam_done_0:
	s_waitcnt lgkmcnt(0)
	s_barrier
	s_cmp_gt_u32 s18, 7
	s_cbranch_scc1 .Las_adv_0
	s_cmp_gt_u32 s18, 4
	s_cbranch_scc1 .Las_w1_0
	s_waitcnt vmcnt(4)
	s_branch .Las_w3_0
.Las_w1_0:
	s_cmp_gt_u32 s18, 5
	s_cbranch_scc1 .Las_w2_0
	s_waitcnt vmcnt(3)
	s_branch .Las_w3_0

; #define ATT_BAR() do { asm volatile("s_waitcnt lgkmcnt(0)" ::: "memory"); __builtin_amdgcn_s_barrier(); asm volatile("" ::: "memory"); } while (0)
; #define ATT_LD(j, KR, VR) do { KR = *(const u32x4*)(Kb + (kg0 + (long)(j) * 64 * D)); VR = *(const u32x4*)(Vt + (vg0 + (long)(j) * 64)); } while (0)
; #define ATT_ST(j, KR, VR) do { LAS unsigned char* kd_ = lds + ATT_KS + ((j) & 3) * KS_TILE + lr * KS_PITCH + pc * 16; LAS unsigned char* vd_ = lds + ATT_VS + ((j) & 3) * VS_TILE + lr * VS_PITCH + (pc >> 1) * 32 + (pc & 1) * 8;     \
;         *(LAS u32x4*)kd_ = KR; *(LAS u32x2*)vd_ = (u32x2){VR.x, VR.y}; *(LAS u32x2*)(vd_ + 16) = (u32x2){VR.z, VR.w}; } while (0)
; __device__ __forceinline__ void attn_phase(LAS unsigned char* lds, const bf16_t* Q, const bf16_t* Kb, const bf16_t* Vt, bf16_t* O, const float* relb, const float* qn, const float* kn, int vcu, int G) {
;     ...
;         for (int g = jlo; g <= 12; ++g) {
;             const int bcg = g - cw, bcp = bcg - 1;
;             const bool actg = (g <= 11) && bcg >= 0 && bcg <= 8, actp = (g - 1 >= jlo) && bcp >= 0 && bcp <= 8;
;             if (actg) ATT_QK(g, bcg, sc0, sc1);
;             if (actp) ATT_PV(g - 1, pw);
;             ATT_BAR();
;             if (g + 2 <= 11) ATT_ST(g + 2, kreg, vreg);
;             if (g + 3 <= 11) ATT_LD(g + 3, kreg, vreg);
;             if (actg) ATT_SM(sc0, sc1, pw);
;             ATT_BAR();
;         }
.Las_w3_0:
	s_add_i32 s20, s18, 5
	s_cmp_lt_u32 s20, s40
	s_cbranch_scc1 .Las_ldk_0
	s_cmp_gt_u32 s18, 6
	s_cbranch_scc1 .Las_ldk_0
	s_add_i32 s21, s20, -6
	s_cmp_gt_u32 s20, 5
	s_cselect_b32 s21, s21, s20
	s_mul_i32 s41, s21, 0x2400
	s_cmp_gt_u32 s21, 3
	s_cselect_b32 s21, 0xe400, 0
	s_cselect_b32 s53, 0x4800, 0
	s_add_i32 s41, s41, s21
	s_sub_i32 s53, s41, s53
	s_add_i32 s53, s53, 0x9000
	v_add_u32_e32 v14, s41, v151
	s_nop 0
	ds_write_b128 v14, v[226:229]
.Las_ldk_0:
	s_add_i32 s20, s18, 4
	s_cmp_lt_u32 s20, s40
	s_cbranch_scc1 .Las_ldv_0
	s_add_i32 s21, s20, -6
	s_cmp_gt_u32 s20, 5
	s_cselect_b32 s21, s21, s20
	s_mul_i32 s41, s21, 0x2400
	s_cmp_gt_u32 s21, 3
	s_cselect_b32 s21, 0xe400, 0
	s_cselect_b32 s53, 0x4800, 0
	s_add_i32 s41, s41, s21
	s_sub_i32 s53, s41, s53
	s_add_i32 s53, s53, 0x9000
	v_add_u32_e32 v15, s53, v152
	s_nop 0
	ds_write2_b64 v15, v[222:223], v[224:225] offset1:2
.Las_ldv_0:
	s_add_i32 s20, s18, 8
	s_cmp_lt_u32 s20, s40
	s_cbranch_scc1 .Las_ldv2_0
	s_cmp_gt_u32 s18, 3
	s_cbranch_scc1 .Las_ldv2_0
	global_load_dwordx4 v[226:229], v[140:141], off
.Las_ldv2_0:
	s_add_i32 s20, s18, 7
	s_cmp_lt_u32 s20, s40
	s_cbranch_scc1 .Las_adv_0
	s_cmp_gt_u32 s18, 4
	s_cbranch_scc1 .Las_adv_0
	global_load_dwordx4 v[222:225], v[138:139], off
.Las_adv_0:
	v_lshl_add_u64 v[140:141], v[140:141], 0, s[44:45]
	v_lshl_add_u64 v[138:139], v[138:139], 0, s[62:63]
	s_and_b64 vcc, exec, s[76:77]
	s_cbranch_vccnz .Las_end_0
	v_exp_f32_e32 v16, v16
	v_exp_f32_e32 v32, v32
	v_exp_f32_e32 v17, v17
	v_exp_f32_e32 v33, v33
	v_exp_f32_e32 v18, v18
	v_exp_f32_e32 v34, v34
	v_exp_f32_e32 v19, v19
	v_exp_f32_e32 v35, v35
	v_add_f32_e32 v11, 0, v16
	v_add_f32_e32 v10, 0, v32
	v_add_f32_e32 v11, v11, v17
	v_add_f32_e32 v10, v10, v33
	v_add_f32_e32 v11, v11, v18
	v_add_f32_e32 v10, v10, v34
	v_add_f32_e32 v11, v11, v19
	v_add_f32_e32 v10, v10, v35
	v_exp_f32_e32 v20, v20
	v_exp_f32_e32 v36, v36
	v_exp_f32_e32 v21, v21
	v_exp_f32_e32 v37, v37
	v_exp_f32_e32 v22, v22
	v_exp_f32_e32 v38, v38
	v_exp_f32_e32 v23, v23
	v_exp_f32_e32 v39, v39
	v_add_f32_e32 v11, v11, v20
	v_add_f32_e32 v10, v10, v36
	v_add_f32_e32 v11, v11, v21
	v_add_f32_e32 v10, v10, v37
	v_add_f32_e32 v11, v11, v22
	v_add_f32_e32 v10, v10, v38
	v_add_f32_e32 v11, v11, v23
	v_add_f32_e32 v10, v10, v39
	v_exp_f32_e32 v24, v24
	v_exp_f32_e32 v40, v40
	v_exp_f32_e32 v25, v25
	v_exp_f32_e32 v41, v41
	v_exp_f32_e32 v26, v26
	v_exp_f32_e32 v42, v42
	v_exp_f32_e32 v27, v27
	v_exp_f32_e32 v43, v43
	v_add_f32_e32 v11, v11, v24
	v_add_f32_e32 v10, v10, v40
	v_add_f32_e32 v11, v11, v25
	v_add_f32_e32 v10, v10, v41
	v_add_f32_e32 v11, v11, v26
	v_add_f32_e32 v10, v10, v42
	v_add_f32_e32 v11, v11, v27
	v_add_f32_e32 v10, v10, v43
	v_exp_f32_e32 v28, v28
	v_exp_f32_e32 v44, v44
	v_exp_f32_e32 v29, v29
	v_exp_f32_e32 v45, v45
	v_exp_f32_e32 v30, v30
	v_exp_f32_e32 v46, v46
	v_exp_f32_e32 v31, v31
	v_exp_f32_e32 v47, v47
	v_add_f32_e32 v11, v11, v28
	v_add_f32_e32 v10, v10, v44
	v_add_f32_e32 v11, v11, v29
	v_add_f32_e32 v10, v10, v45
	v_add_f32_e32 v11, v11, v30
	v_add_f32_e32 v10, v10, v46
	v_add_f32_e32 v11, v11, v31
	v_add_f32_e32 v10, v10, v47
	v_cvt_pk_bf16_f32 v104, v16, v17
	v_cvt_pk_bf16_f32 v105, v18, v19
	v_cvt_pk_bf16_f32 v106, v20, v21
	v_cvt_pk_bf16_f32 v107, v22, v23
	v_cvt_pk_bf16_f32 v108, v32, v33
	v_cvt_pk_bf16_f32 v109, v34, v35
	v_cvt_pk_bf16_f32 v110, v36, v37
	v_cvt_pk_bf16_f32 v111, v38, v39
	v_cvt_pk_bf16_f32 v112, v24, v25
	v_cvt_pk_bf16_f32 v113, v26, v27
	v_cvt_pk_bf16_f32 v114, v28, v29
	v_cvt_pk_bf16_f32 v115, v30, v31
	v_cvt_pk_bf16_f32 v116, v40, v41
	v_cvt_pk_bf16_f32 v117, v42, v43
	v_cvt_pk_bf16_f32 v118, v44, v45
	v_cvt_pk_bf16_f32 v119, v46, v47
	v_add_f32_e32 v1, v10, v11
	v_add_f32_e32 v131, v131, v1
.Las_end_0:
	s_cmp_gt_u32 s18, 8
	s_cbranch_scc1 .Lag_exit
	s_add_i32 s18, s18, 1
	s_mov_b32 s19, s18
	v_add_u32_e32 v133, 0x100, v133
	s_sub_i32 s20, s19, s28
	s_cmp_lt_u32 s19, 9
	s_cselect_b64 s[42:43], -1, 0
	s_cmp_ge_u32 s20, s40
	s_cselect_b64 s[48:49], -1, 0
	s_and_b64 s[42:43], s[42:43], s[48:49]
	s_not_b64 s[76:77], s[42:43]
	s_add_i32 s21, s19, -1
	s_cmp_lt_u32 s21, 9
	s_cselect_b64 s[48:49], -1, 0
	s_cmp_gt_u32 s20, s40
	s_cselect_b64 s[80:81], -1, 0
	s_and_b64 s[48:49], s[48:49], s[80:81]
	s_add_i32 s21, s20, -1
	s_add_i32 s80, s21, -6
	s_cmp_gt_u32 s21, 5
	s_cselect_b32 s80, s80, s21
	s_mul_i32 s41, s80, 0x2400
	s_cmp_gt_u32 s80, 3
	s_cselect_b32 s80, 0xe400, 0
	s_cselect_b32 s53, 0x4800, 0
	s_add_i32 s41, s41, s80
	s_sub_i32 s53, s41, s53
	s_add_i32 s53, s53, 0x9000
	v_add_u32_e32 v217, s53, v153
	s_add_i32 s80, s20, -6
	s_cmp_gt_u32 s20, 5
	s_cselect_b32 s80, s80, s20
	s_mul_i32 s41, s80, 0x2400
	s_cmp_gt_u32 s80, 3
	s_cselect_b32 s80, 0xe400, 0
	s_cselect_b32 s53, 0x4800, 0
	s_add_i32 s41, s41, s80
	s_sub_i32 s53, s41, s53
	s_add_i32 s53, s53, 0x9000
	v_add_u32_e32 v1, s41, v153
	s_and_b64 s[80:81], exec, s[42:43]
	s_cbranch_scc0 .Lpf_none_l0
	s_waitcnt lgkmcnt(0)
	s_cmp_lt_u32 s19, 4
	s_cbranch_scc0 .Lpf_tbl_l0
	ds_read_b128 v[2:5], v1
	ds_read_b128 v[6:9], v1 offset:4608
	ds_read_b128 v[158:161], v1 offset:32
	ds_read_b128 v[162:165], v1 offset:4640
	ds_read_b128 v[166:169], v1 offset:64
	ds_read_b128 v[194:197], v1 offset:4672
	ds_read_b128 v[198:201], v1 offset:96
	ds_read_b128 v[202:205], v1 offset:4704
	v_mov_b64_e32 v[16:17], v[246:247]
	v_mov_b64_e32 v[18:19], v[246:247]
	v_mov_b64_e32 v[20:21], v[246:247]
	v_mov_b64_e32 v[22:23], v[246:247]
	v_mov_b64_e32 v[24:25], v[246:247]
	v_mov_b64_e32 v[26:27], v[246:247]
	v_mov_b64_e32 v[28:29], v[246:247]
	v_mov_b64_e32 v[30:31], v[246:247]
	v_mov_b64_e32 v[32:33], v[246:247]
	v_mov_b64_e32 v[34:35], v[246:247]
	v_mov_b64_e32 v[36:37], v[246:247]
	v_mov_b64_e32 v[38:39], v[246:247]
	v_mov_b64_e32 v[40:41], v[246:247]
	v_mov_b64_e32 v[42:43], v[246:247]
	v_mov_b64_e32 v[44:45], v[246:247]
	v_mov_b64_e32 v[46:47], v[246:247]
	s_waitcnt lgkmcnt(8)
	s_branch .Lpf_done_l0

; #define ATT_BAR() do { asm volatile("s_waitcnt lgkmcnt(0)" ::: "memory"); __builtin_amdgcn_s_barrier(); asm volatile("" ::: "memory"); } while (0)
; #define ATT_LD(j, KR, VR) do { KR = *(const u32x4*)(Kb + (kg0 + (long)(j) * 64 * D)); VR = *(const u32x4*)(Vt + (vg0 + (long)(j) * 64)); } while (0)
; #define ATT_ST(j, KR, VR) do { LAS unsigned char* kd_ = lds + ATT_KS + ((j) & 3) * KS_TILE + lr * KS_PITCH + pc * 16; LAS unsigned char* vd_ = lds + ATT_VS + ((j) & 3) * VS_TILE + lr * VS_PITCH + (pc >> 1) * 32 + (pc & 1) * 8;     \
;         *(LAS u32x4*)kd_ = KR; *(LAS u32x2*)vd_ = (u32x2){VR.x, VR.y}; *(LAS u32x2*)(vd_ + 16) = (u32x2){VR.z, VR.w}; } while (0)
; __device__ __forceinline__ void attn_phase(LAS unsigned char* lds, const bf16_t* Q, const bf16_t* Kb, const bf16_t* Vt, bf16_t* O, const float* relb, const float* qn, const float* kn, int vcu, int G) {
;     ...
;         for (int g = jlo; g <= 12; ++g) {
;             const int bcg = g - cw, bcp = bcg - 1;
;             const bool actg = (g <= 11) && bcg >= 0 && bcg <= 8, actp = (g - 1 >= jlo) && bcp >= 0 && bcp <= 8;
;             if (actg) ATT_QK(g, bcg, sc0, sc1);
;             if (actp) ATT_PV(g - 1, pw);
;             ATT_BAR();
;             if (g + 2 <= 11) ATT_ST(g + 2, kreg, vreg);
;             if (g + 3 <= 11) ATT_LD(g + 3, kreg, vreg);
;             if (actg) ATT_SM(sc0, sc1, pw);
;             ATT_BAR();
;         }
.Lpf_done_l0:
	s_barrier

; #define ATT_BAR() do { asm volatile("s_waitcnt lgkmcnt(0)" ::: "memory"); __builtin_amdgcn_s_barrier(); asm volatile("" ::: "memory"); } while (0)
; #define ATT_LD(j, KR, VR) do { KR = *(const u32x4*)(Kb + (kg0 + (long)(j) * 64 * D)); VR = *(const u32x4*)(Vt + (vg0 + (long)(j) * 64)); } while (0)
; #define ATT_ST(j, KR, VR) do { LAS unsigned char* kd_ = lds + ATT_KS + ((j) & 3) * KS_TILE + lr * KS_PITCH + pc * 16; LAS unsigned char* vd_ = lds + ATT_VS + ((j) & 3) * VS_TILE + lr * VS_PITCH + (pc >> 1) * 32 + (pc & 1) * 8;     \
;         *(LAS u32x4*)kd_ = KR; *(LAS u32x2*)vd_ = (u32x2){VR.x, VR.y}; *(LAS u32x2*)(vd_ + 16) = (u32x2){VR.z, VR.w}; } while (0)
; __device__ __forceinline__ void attn_phase(LAS unsigned char* lds, const bf16_t* Q, const bf16_t* Kb, const bf16_t* Vt, bf16_t* O, const float* relb, const float* qn, const float* kn, int vcu, int G) {
;     ...
;         for (int g = jlo; g <= 12; ++g) {
;             const int bcg = g - cw, bcp = bcg - 1;
;             const bool actg = (g <= 11) && bcg >= 0 && bcg <= 8, actp = (g - 1 >= jlo) && bcp >= 0 && bcp <= 8;
;             if (actg) ATT_QK(g, bcg, sc0, sc1);
;             if (actp) ATT_PV(g - 1, pw);
;             ATT_BAR();
;             if (g + 2 <= 11) ATT_ST(g + 2, kreg, vreg);
;             if (g + 3 <= 11) ATT_LD(g + 3, kreg, vreg);
;             if (actg) ATT_SM(sc0, sc1, pw);
;             ATT_BAR();
;         }
.Las_w3_1:
	s_add_i32 s20, s18, 5
	s_cmp_lt_u32 s20, s40
	s_cbranch_scc1 .Las_ldk_1
	s_cmp_gt_u32 s18, 6
	s_cbranch_scc1 .Las_ldk_1
	s_add_i32 s21, s20, -6
	s_cmp_gt_u32 s20, 5
	s_cselect_b32 s21, s21, s20
	s_mul_i32 s41, s21, 0x2400
	s_cmp_gt_u32 s21, 3
	s_cselect_b32 s21, 0xe400, 0
	s_cselect_b32 s53, 0x4800, 0
	s_add_i32 s41, s41, s21
	s_sub_i32 s53, s41, s53
	s_add_i32 s53, s53, 0x9000
	v_add_u32_e32 v14, s41, v151
	s_nop 0
	ds_write_b128 v14, v[96:99]
.Las_ldk_1:
	s_add_i32 s20, s18, 4
	s_cmp_lt_u32 s20, s40
	s_cbranch_scc1 .Las_ldv_1
	s_add_i32 s21, s20, -6
	s_cmp_gt_u32 s20, 5
	s_cselect_b32 s21, s21, s20
	s_mul_i32 s41, s21, 0x2400
	s_cmp_gt_u32 s21, 3
	s_cselect_b32 s21, 0xe400, 0
	s_cselect_b32 s53, 0x4800, 0
	s_add_i32 s41, s41, s21
	s_sub_i32 s53, s41, s53
	s_add_i32 s53, s53, 0x9000
	v_add_u32_e32 v15, s53, v152
	s_nop 0
	ds_write2_b64 v15, v[230:231], v[232:233] offset1:2
.Las_ldv_1:
	s_add_i32 s20, s18, 8
	s_cmp_lt_u32 s20, s40
	s_cbranch_scc1 .Las_ldv2_1
	s_cmp_gt_u32 s18, 3
	s_cbranch_scc1 .Las_ldv2_1
	global_load_dwordx4 v[96:99], v[140:141], off
.Las_ldv2_1:
	s_add_i32 s20, s18, 7
	s_cmp_lt_u32 s20, s40
	s_cbranch_scc1 .Las_adv_1
	s_cmp_gt_u32 s18, 4
	s_cbranch_scc1 .Las_adv_1
	global_load_dwordx4 v[230:233], v[138:139], off

; #define ATT_BAR() do { asm volatile("s_waitcnt lgkmcnt(0)" ::: "memory"); __builtin_amdgcn_s_barrier(); asm volatile("" ::: "memory"); } while (0)
; #define ATT_LD(j, KR, VR) do { KR = *(const u32x4*)(Kb + (kg0 + (long)(j) * 64 * D)); VR = *(const u32x4*)(Vt + (vg0 + (long)(j) * 64)); } while (0)
; #define ATT_ST(j, KR, VR) do { LAS unsigned char* kd_ = lds + ATT_KS + ((j) & 3) * KS_TILE + lr * KS_PITCH + pc * 16; LAS unsigned char* vd_ = lds + ATT_VS + ((j) & 3) * VS_TILE + lr * VS_PITCH + (pc >> 1) * 32 + (pc & 1) * 8;     \
;         *(LAS u32x4*)kd_ = KR; *(LAS u32x2*)vd_ = (u32x2){VR.x, VR.y}; *(LAS u32x2*)(vd_ + 16) = (u32x2){VR.z, VR.w}; } while (0)
; __device__ __forceinline__ void attn_phase(LAS unsigned char* lds, const bf16_t* Q, const bf16_t* Kb, const bf16_t* Vt, bf16_t* O, const float* relb, const float* qn, const float* kn, int vcu, int G) {
;     ...
;         for (int g = jlo; g <= 12; ++g) {
;             const int bcg = g - cw, bcp = bcg - 1;
;             const bool actg = (g <= 11) && bcg >= 0 && bcg <= 8, actp = (g - 1 >= jlo) && bcp >= 0 && bcp <= 8;
;             if (actg) ATT_QK(g, bcg, sc0, sc1);
;             if (actp) ATT_PV(g - 1, pw);
;             ATT_BAR();
;             if (g + 2 <= 11) ATT_ST(g + 2, kreg, vreg);
;             if (g + 3 <= 11) ATT_LD(g + 3, kreg, vreg);
;             if (actg) ATT_SM(sc0, sc1, pw);
;             ATT_BAR();
;         }
.Las_w3_2:
	s_add_i32 s20, s18, 5
	s_cmp_lt_u32 s20, s40
	s_cbranch_scc1 .Las_ldk_2
	s_cmp_gt_u32 s18, 6
	s_cbranch_scc1 .Las_ldk_2
	s_add_i32 s21, s20, -6
	s_cmp_gt_u32 s20, 5
	s_cselect_b32 s21, s21, s20
	s_mul_i32 s41, s21, 0x2400
	s_cmp_gt_u32 s21, 3
	s_cselect_b32 s21, 0xe400, 0
	s_cselect_b32 s53, 0x4800, 0
	s_add_i32 s41, s41, s21
	s_sub_i32 s53, s41, s53
	s_add_i32 s53, s53, 0x9000
	v_add_u32_e32 v14, s41, v151
	s_nop 0
	ds_write_b128 v14, v[218:221]
.Las_ldk_2:
	s_add_i32 s20, s18, 4
	s_cmp_lt_u32 s20, s40
	s_cbranch_scc1 .Las_ldv_2
	s_add_i32 s21, s20, -6
	s_cmp_gt_u32 s20, 5
	s_cselect_b32 s21, s21, s20
	s_mul_i32 s41, s21, 0x2400
	s_cmp_gt_u32 s21, 3
	s_cselect_b32 s21, 0xe400, 0
	s_cselect_b32 s53, 0x4800, 0
	s_add_i32 s41, s41, s21
	s_sub_i32 s53, s41, s53
	s_add_i32 s53, s53, 0x9000
	v_add_u32_e32 v15, s53, v152
	s_nop 0
	ds_write2_b64 v15, v[100:101], v[102:103] offset1:2
.Las_ldv_2:
	s_add_i32 s20, s18, 8
	s_cmp_lt_u32 s20, s40
	s_cbranch_scc1 .Las_ldv2_2
	s_cmp_gt_u32 s18, 3
	s_cbranch_scc1 .Las_ldv2_2
	global_load_dwordx4 v[218:221], v[140:141], off
.Las_ldv2_2:
	s_add_i32 s20, s18, 7
	s_cmp_lt_u32 s20, s40
	s_cbranch_scc1 .Las_adv_2
	s_cmp_gt_u32 s18, 4
	s_cbranch_scc1 .Las_adv_2
	global_load_dwordx4 v[100:103], v[138:139], off

; #define ATT_BAR() do { asm volatile("s_waitcnt lgkmcnt(0)" ::: "memory"); __builtin_amdgcn_s_barrier(); asm volatile("" ::: "memory"); } while (0)
; #define ATT_LD(j, KR, VR) do { KR = *(const u32x4*)(Kb + (kg0 + (long)(j) * 64 * D)); VR = *(const u32x4*)(Vt + (vg0 + (long)(j) * 64)); } while (0)
; #define ATT_ST(j, KR, VR) do { LAS unsigned char* kd_ = lds + ATT_KS + ((j) & 3) * KS_TILE + lr * KS_PITCH + pc * 16; LAS unsigned char* vd_ = lds + ATT_VS + ((j) & 3) * VS_TILE + lr * VS_PITCH + (pc >> 1) * 32 + (pc & 1) * 8;     \
;         *(LAS u32x4*)kd_ = KR; *(LAS u32x2*)vd_ = (u32x2){VR.x, VR.y}; *(LAS u32x2*)(vd_ + 16) = (u32x2){VR.z, VR.w}; } while (0)
; __device__ __forceinline__ void attn_phase(LAS unsigned char* lds, const bf16_t* Q, const bf16_t* Kb, const bf16_t* Vt, bf16_t* O, const float* relb, const float* qn, const float* kn, int vcu, int G) {
;     ...
;         for (int g = jlo; g <= 12; ++g) {
;             const int bcg = g - cw, bcp = bcg - 1;
;             const bool actg = (g <= 11) && bcg >= 0 && bcg <= 8, actp = (g - 1 >= jlo) && bcp >= 0 && bcp <= 8;
;             if (actg) ATT_QK(g, bcg, sc0, sc1);
;             if (actp) ATT_PV(g - 1, pw);
;             ATT_BAR();
;             if (g + 2 <= 11) ATT_ST(g + 2, kreg, vreg);
;             if (g + 3 <= 11) ATT_LD(g + 3, kreg, vreg);
;             if (actg) ATT_SM(sc0, sc1, pw);
;             ATT_BAR();
;         }
;         if (half == 0) ATT_BAR();
.Lpf_done_l2:
	s_barrier
	s_branch .Lag_0
	s_branch .Lag_exit
.Lprobe_stub:
	s_waitcnt lgkmcnt(0)
	s_barrier
	s_andn2_b64 vcc, exec, s[0:1]
	s_cbranch_vccnz .Lag_exit
	s_barrier
.Lag_exit:
	s_waitcnt lgkmcnt(0)
	s_barrier
.LBB0_471:
	s_and_b64 vcc, exec, s[36:37]
	s_cbranch_vccz .LBB0_435
	s_waitcnt lgkmcnt(0)
	s_barrier
	s_branch .LBB0_435

; #define LAS __attribute__((address_space(3)))
; __global__ void __launch_bounds__(512, 2) fwd_megakernel(Params p) {
;     extern __shared__ __attribute__((aligned(16))) unsigned char lds_raw[];
;     LAS unsigned char* lds = (LAS unsigned char*)lds_raw;
	.amdhsa_kernel _Z14fwd_megakernel6Params
		.amdhsa_group_segment_fixed_size 8192
		.amdhsa_private_segment_fixed_size 0
		.amdhsa_kernarg_size 400
		.amdhsa_user_sgpr_count 2
		.amdhsa_user_sgpr_dispatch_ptr 0
		.amdhsa_user_sgpr_queue_ptr 0
		.amdhsa_user_sgpr_kernarg_segment_ptr 1
		.amdhsa_user_sgpr_dispatch_id 0
		.amdhsa_user_sgpr_kernarg_preload_length 0
		.amdhsa_user_sgpr_kernarg_preload_offset 0
		.amdhsa_user_sgpr_private_segment_size 0
		.amdhsa_uses_dynamic_stack 0
		.amdhsa_enable_private_segment 0
		.amdhsa_system_sgpr_workgroup_id_x 1
		.amdhsa_system_sgpr_workgroup_id_y 0
		.amdhsa_system_sgpr_workgroup_id_z 0
		.amdhsa_system_sgpr_workgroup_info 0
		.amdhsa_system_vgpr_workitem_id 2
		.amdhsa_next_free_vgpr 256
		.amdhsa_next_free_sgpr 102
		.amdhsa_accum_offset 256
		.amdhsa_reserve_vcc 1
		.amdhsa_float_round_mode_32 0
		.amdhsa_float_round_mode_16_64 0
		.amdhsa_float_denorm_mode_32 3
		.amdhsa_float_denorm_mode_16_64 3
		.amdhsa_dx10_clamp 1
		.amdhsa_ieee_mode 1
		.amdhsa_fp16_overflow 0
		.amdhsa_tg_split 0
		.amdhsa_exception_fp_ieee_invalid_op 0
		.amdhsa_exception_fp_denorm_src 0
		.amdhsa_exception_fp_ieee_div_zero 0
		.amdhsa_exception_fp_ieee_overflow 0
		.amdhsa_exception_fp_ieee_underflow 0
		.amdhsa_exception_fp_ieee_inexact 0
		.amdhsa_exception_int_div_zero 0
	.end_amdhsa_kernel

; #define LAS __attribute__((address_space(3)))
; __global__ void __launch_bounds__(512, 2) fwd_megakernel(Params p) {
;     extern __shared__ __attribute__((aligned(16))) unsigned char lds_raw[];
;     LAS unsigned char* lds = (LAS unsigned char*)lds_raw;
amdhsa.kernels:
  - .agpr_count:     0
    .args:
      - .offset:         0
        .size:           144
        .value_kind:     by_value
      - .offset:         144
        .size:           4
        .value_kind:     hidden_block_count_x
      - .offset:         148
        .size:           4
        .value_kind:     hidden_block_count_y
      - .offset:         152
        .size:           4
        .value_kind:     hidden_block_count_z
      - .offset:         156
        .size:           2
        .value_kind:     hidden_group_size_x
      - .offset:         158
        .size:           2
        .value_kind:     hidden_group_size_y
      - .offset:         160
        .size:           2
        .value_kind:     hidden_group_size_z
      - .offset:         162
        .size:           2
        .value_kind:     hidden_remainder_x
      - .offset:         164
        .size:           2
        .value_kind:     hidden_remainder_y
      - .offset:         166
        .size:           2
        .value_kind:     hidden_remainder_z
      - .offset:         184
        .size:           8
        .value_kind:     hidden_global_offset_x
      - .offset:         192
        .size:           8
        .value_kind:     hidden_global_offset_y
      - .offset:         200
        .size:           8
        .value_kind:     hidden_global_offset_z
      - .offset:         208
        .size:           2
        .value_kind:     hidden_grid_dims
      - .offset:         232
        .size:           8
        .value_kind:     hidden_multigrid_sync_arg
      - .offset:         264
        .size:           4
        .value_kind:     hidden_dynamic_lds_size
    .group_segment_fixed_size: 8192
    .kernarg_segment_align: 8
    .kernarg_segment_size: 400
    .language:       OpenCL C
    .language_version:
      - 2
      - 0
    .max_flat_workgroup_size: 512
    .name:           _Z14fwd_megakernel6Params
    .private_segment_fixed_size: 0
    .sgpr_count:     108
    .sgpr_spill_count: 312
    .symbol:         _Z14fwd_megakernel6Params.kd
    .uniform_work_group_size: 1
    .uses_dynamic_stack: false
    .vgpr_count:     256
    .vgpr_spill_count: 0
    .wavefront_size: 64
